# hot loop heads (six GEMM K-loops, attention step loop, mLSTM chunk loop) aligned to 64-byte boundaries
# speedup vs baseline: 1.0090x; 1.0024x over previous
.LBB0_214:
	s_add_u32 s24, s24, 0x40080
	s_addc_u32 s25, s25, 0
	s_add_u32 s48, s26, 0x100
	s_addc_u32 s49, s27, 0
	s_mov_b32 s50, -2
	s_waitcnt lgkmcnt(0)
	v_xor_b32_e32 v246, 64, v153
	v_xor_b32_e32 v247, 64, v149
	v_add_u32_e32 v248, s42, v247
	v_add_u32_e32 v249, s43, v247
	ds_read_b128 v[144:147], v151
	ds_read_b128 v[154:157], v248
	ds_read_b128 v[158:161], v151 offset:2048
	ds_read_b128 v[162:165], v248 offset:2048
	ds_read_b128 v[166:169], v152
	ds_read_b128 v[170:173], v249
	ds_read_b128 v[174:177], v152 offset:2048
	ds_read_b128 v[178:181], v249 offset:2048
	s_add_u32 s26, s24, 0xfffc0080
	s_addc_u32 s27, s25, -1
	s_cmp_eq_u32 s50, 12
	s_cselect_b32 s29, s17, s27
	s_cselect_b32 s28, s46, s26
	s_cselect_b32 s27, s15, s49
	s_cselect_b32 s26, s47, s48
	v_lshl_add_u64 v[214:215], s[24:25], 0, v[136:137]
	s_add_i32 m0, s23, 0xc000
	ds_read_b128 v[182:185], v153
	ds_read_b128 v[186:189], v246
	ds_read_b128 v[190:193], v153 offset:2048
	ds_read_b128 v[194:197], v246 offset:2048
	ds_read_b128 v[198:201], v153 offset:4096
	ds_read_b128 v[202:205], v246 offset:4096
	ds_read_b128 v[206:209], v153 offset:6144
	ds_read_b128 v[210:213], v246 offset:6144
	global_load_lds_dwordx4 v[214:215], off
	v_lshl_add_u64 v[214:215], s[24:25], 0, v[138:139]
	s_add_i32 m0, s23, 0xe000
	s_nop 0
	global_load_lds_dwordx4 v[214:215], off
	s_waitcnt vmcnt(8)
	s_waitcnt lgkmcnt(0)
	s_barrier
	s_waitcnt lgkmcnt(0)
	v_mfma_f32_16x16x32_bf16 v[124:127], v[144:147], v[182:185], 0
	s_add_i32 s37, s37, 1
	s_mul_i32 s6, s37, s38
	s_mul_hi_u32 s7, s37, s41
	v_mfma_f32_16x16x32_bf16 v[120:123], v[158:161], v[182:185], 0
	s_add_i32 s7, s7, s6
	s_mul_i32 s6, s37, s41
	s_add_u32 s18, s6, s96
	v_mfma_f32_16x16x32_bf16 v[108:111], v[144:147], v[190:193], 0
	s_addc_u32 s19, s7, s31
	v_cmp_lt_i64_e64 s[6:7], s[18:19], v[140:141]
	s_ashr_i32 s14, s18, 31
	v_mfma_f32_16x16x32_bf16 v[104:107], v[158:161], v[190:193], 0
	s_lshr_b32 s14, s14, 29
	s_add_i32 s14, s18, s14
	s_ashr_i32 s15, s14, 3
	v_mfma_f32_16x16x32_bf16 v[92:95], v[144:147], v[198:201], 0
	s_and_b32 s14, s14, -8
	s_sub_i32 s14, s18, s14
	s_cmp_lt_i32 s14, 0
	v_mfma_f32_16x16x32_bf16 v[88:91], v[158:161], v[198:201], 0
	s_cselect_b32 s16, s33, 0x160
	s_mul_i32 s14, s14, s16
	s_add_i32 s14, s14, s15
	v_mfma_f32_16x16x32_bf16 v[76:79], v[144:147], v[206:209], 0
	s_mul_hi_i32 s15, s14, 0x2e8ba2e9
	s_lshr_b32 s16, s15, 31
	s_ashr_i32 s15, s15, 5
	v_mfma_f32_16x16x32_bf16 v[72:75], v[158:161], v[206:209], 0
	s_add_i32 s15, s15, s16
	s_lshl_b32 s16, s15, 3
	s_sub_i32 s17, 0x80, s16
	v_mfma_f32_16x16x32_bf16 v[124:127], v[154:157], v[186:189], v[124:127]
	s_min_i32 s17, s17, 8
	s_abs_i32 s18, s17
	v_cvt_f32_u32_e32 v252, s18
	v_mfma_f32_16x16x32_bf16 v[120:123], v[162:165], v[186:189], v[120:123]
	s_sub_i32 s20, 0, s18
	s_mulk_i32 s15, 0xb0
	s_sub_i32 s15, s14, s15
	v_mfma_f32_16x16x32_bf16 v[108:111], v[154:157], v[194:197], v[108:111]
	v_rcp_iflag_f32_e32 v252, v252
	s_abs_i32 s14, s15
	s_xor_b32 s19, s15, s17
	v_mfma_f32_16x16x32_bf16 v[104:107], v[162:165], v[194:197], v[104:107]
	s_ashr_i32 s19, s19, 31
	v_mul_f32_e32 v252, 0x4f7ffffe, v252
	v_cvt_u32_f32_e32 v252, v252
	v_mfma_f32_16x16x32_bf16 v[92:95], v[154:157], v[202:205], v[92:95]
	s_nop 0
	v_readfirstlane_b32 s21, v252
	s_mul_i32 s20, s20, s21
	v_mfma_f32_16x16x32_bf16 v[88:91], v[162:165], v[202:205], v[88:91]
	s_mul_hi_u32 s20, s21, s20
	s_add_i32 s21, s21, s20
	s_mul_hi_u32 s20, s14, s21
	v_mfma_f32_16x16x32_bf16 v[76:79], v[154:157], v[210:213], v[76:79]
	s_mul_i32 s21, s20, s18
	s_sub_i32 s14, s14, s21
	s_add_i32 s98, s20, 1
	v_mfma_f32_16x16x32_bf16 v[72:75], v[162:165], v[210:213], v[72:75]
	s_sub_i32 s21, s14, s18
	s_cmp_ge_u32 s14, s18
	s_cselect_b32 s20, s98, s20
	v_mfma_f32_16x16x32_bf16 v[116:119], v[166:169], v[182:185], 0
	s_cselect_b32 s14, s21, s14
	s_add_i32 s21, s20, 1
	s_cmp_ge_u32 s14, s18
	v_mfma_f32_16x16x32_bf16 v[112:115], v[174:177], v[182:185], 0
	s_cselect_b32 s14, s21, s20
	s_xor_b32 s14, s14, s19
	s_sub_i32 s14, s14, s19
	v_mfma_f32_16x16x32_bf16 v[100:103], v[166:169], v[190:193], 0
	s_mul_i32 s17, s14, s17
	s_sub_i32 s15, s15, s17
	s_add_i32 s16, s16, s15
	v_mfma_f32_16x16x32_bf16 v[96:99], v[174:177], v[190:193], 0
	s_ashr_i32 s17, s16, 31
	s_lshl_b64 s[18:19], s[16:17], 19
	s_add_u32 s18, s90, s18
	v_mfma_f32_16x16x32_bf16 v[84:87], v[166:169], v[198:201], 0
	s_addc_u32 s19, s91, s19
	s_and_b64 s[20:21], s[6:7], exec
	s_cselect_b32 s17, s19, s25
	v_mfma_f32_16x16x32_bf16 v[80:83], v[174:177], v[198:201], 0
	s_cselect_b32 s46, s18, s24
	s_ashr_i32 s15, s14, 31
	s_lshl_b64 s[20:21], s[14:15], 19
	v_mfma_f32_16x16x32_bf16 v[68:71], v[166:169], v[206:209], 0
	s_add_u32 s20, s2, s20
	s_addc_u32 s21, s3, s21
	s_and_b64 s[98:99], s[6:7], exec
	v_mfma_f32_16x16x32_bf16 v[64:67], v[174:177], v[206:209], 0
	s_cselect_b32 s15, s21, s27
	s_cselect_b32 s47, s20, s26
	v_mfma_f32_16x16x32_bf16 v[116:119], v[170:173], v[186:189], v[116:119]
	v_mfma_f32_16x16x32_bf16 v[112:115], v[178:181], v[186:189], v[112:115]
	v_mfma_f32_16x16x32_bf16 v[100:103], v[170:173], v[194:197], v[100:103]
	v_mfma_f32_16x16x32_bf16 v[96:99], v[178:181], v[194:197], v[96:99]
	v_mfma_f32_16x16x32_bf16 v[84:87], v[170:173], v[202:205], v[84:87]
	v_mfma_f32_16x16x32_bf16 v[80:83], v[178:181], v[202:205], v[80:83]
	v_mfma_f32_16x16x32_bf16 v[68:71], v[170:173], v[210:213], v[68:71]
	v_mfma_f32_16x16x32_bf16 v[64:67], v[178:181], v[210:213], v[64:67]
	s_barrier
	s_add_i32 s51, s42, s30
	v_lshl_add_u64 v[214:215], s[26:27], 0, v[132:133]
	s_mov_b32 m0, s51
	ds_read_b128 v[182:185], v153 offset:16384
	ds_read_b128 v[186:189], v246 offset:16384
	ds_read_b128 v[190:193], v153 offset:18432
	ds_read_b128 v[194:197], v246 offset:18432
	ds_read_b128 v[198:201], v153 offset:20480
	ds_read_b128 v[202:205], v246 offset:20480
	ds_read_b128 v[206:209], v153 offset:22528
	ds_read_b128 v[210:213], v246 offset:22528
	global_load_lds_dwordx4 v[214:215], off
	s_add_i32 m0, s51, 0x2000
	s_add_u32 s52, s26, 0x40000
	v_lshl_add_u64 v[216:217], s[26:27], 0, v[128:129]
	s_addc_u32 s53, s27, 0
	s_add_i32 s51, s43, s30
	global_load_lds_dwordx4 v[216:217], off
	v_lshl_add_u64 v[218:219], s[52:53], 0, v[132:133]
	s_mov_b32 m0, s51
	v_lshl_add_u64 v[220:221], s[28:29], 0, v[130:131]
	global_load_lds_dwordx4 v[218:219], off
	v_lshl_add_u64 v[218:219], s[52:53], 0, v[128:129]
	s_add_i32 m0, s51, 0x2000
	s_nop 0
	global_load_lds_dwordx4 v[218:219], off
	v_lshl_add_u64 v[218:219], s[28:29], 0, v[134:135]
	s_mov_b32 m0, s23
	s_nop 0
	global_load_lds_dwordx4 v[218:219], off
	s_mov_b32 m0, s34
	s_nop 0
	global_load_lds_dwordx4 v[220:221], off
	s_waitcnt vmcnt(8)
	s_waitcnt lgkmcnt(0)
	s_barrier
	s_waitcnt lgkmcnt(0)
	v_mfma_f32_16x16x32_bf16 v[60:63], v[144:147], v[182:185], 0
	v_mfma_f32_16x16x32_bf16 v[56:59], v[158:161], v[182:185], 0
	v_mfma_f32_16x16x32_bf16 v[44:47], v[144:147], v[190:193], 0
	v_mfma_f32_16x16x32_bf16 v[40:43], v[158:161], v[190:193], 0
	v_mfma_f32_16x16x32_bf16 v[28:31], v[144:147], v[198:201], 0
	v_mfma_f32_16x16x32_bf16 v[24:27], v[158:161], v[198:201], 0
	v_mfma_f32_16x16x32_bf16 v[12:15], v[144:147], v[206:209], 0
	v_mfma_f32_16x16x32_bf16 v[8:11], v[158:161], v[206:209], 0
	v_mfma_f32_16x16x32_bf16 v[60:63], v[154:157], v[186:189], v[60:63]
	v_mfma_f32_16x16x32_bf16 v[56:59], v[162:165], v[186:189], v[56:59]
	v_mfma_f32_16x16x32_bf16 v[44:47], v[154:157], v[194:197], v[44:47]
	v_mfma_f32_16x16x32_bf16 v[40:43], v[162:165], v[194:197], v[40:43]
	v_mfma_f32_16x16x32_bf16 v[28:31], v[154:157], v[202:205], v[28:31]
	v_mfma_f32_16x16x32_bf16 v[24:27], v[162:165], v[202:205], v[24:27]
	v_mfma_f32_16x16x32_bf16 v[12:15], v[154:157], v[210:213], v[12:15]
	v_mfma_f32_16x16x32_bf16 v[8:11], v[162:165], v[210:213], v[8:11]
	v_mfma_f32_16x16x32_bf16 v[52:55], v[166:169], v[182:185], 0
	v_mfma_f32_16x16x32_bf16 v[48:51], v[174:177], v[182:185], 0
	v_mfma_f32_16x16x32_bf16 v[36:39], v[166:169], v[190:193], 0
	v_mfma_f32_16x16x32_bf16 v[32:35], v[174:177], v[190:193], 0
	v_mfma_f32_16x16x32_bf16 v[20:23], v[166:169], v[198:201], 0
	v_mfma_f32_16x16x32_bf16 v[16:19], v[174:177], v[198:201], 0
	v_mfma_f32_16x16x32_bf16 v[4:7], v[166:169], v[206:209], 0
	v_mfma_f32_16x16x32_bf16 v[0:3], v[174:177], v[206:209], 0
	v_mfma_f32_16x16x32_bf16 v[52:55], v[170:173], v[186:189], v[52:55]
	v_mfma_f32_16x16x32_bf16 v[48:51], v[178:181], v[186:189], v[48:51]
	v_mfma_f32_16x16x32_bf16 v[36:39], v[170:173], v[194:197], v[36:39]
	v_mfma_f32_16x16x32_bf16 v[32:35], v[178:181], v[194:197], v[32:35]
	v_mfma_f32_16x16x32_bf16 v[20:23], v[170:173], v[202:205], v[20:23]
	v_mfma_f32_16x16x32_bf16 v[16:19], v[178:181], v[202:205], v[16:19]
	v_mfma_f32_16x16x32_bf16 v[4:7], v[170:173], v[210:213], v[4:7]
	v_mfma_f32_16x16x32_bf16 v[0:3], v[178:181], v[210:213], v[0:3]
	s_barrier
	s_add_i32 s51, 0, 0x18000
	s_add_i32 s52, 0, 0x1c000
	v_add_u32_e32 v162, s51, v149
	v_add_u32_e32 v250, s51, v247
	v_add_u32_e32 v178, s52, v149
	v_add_u32_e32 v251, s52, v247
	ds_read_b128 v[144:147], v162
	ds_read_b128 v[154:157], v250
	ds_read_b128 v[158:161], v162 offset:2048
	ds_read_b128 v[162:165], v250 offset:2048
	ds_read_b128 v[166:169], v178
	ds_read_b128 v[170:173], v251
	ds_read_b128 v[174:177], v178 offset:2048
	ds_read_b128 v[178:181], v251 offset:2048
	s_add_u32 s28, s28, 0x40000
	s_addc_u32 s29, s29, 0
	s_mov_b32 m0, s35
	v_lshl_add_u64 v[222:223], s[28:29], 0, v[134:135]
	ds_read_b128 v[182:185], v153 offset:32768
	ds_read_b128 v[186:189], v246 offset:32768
	ds_read_b128 v[190:193], v153 offset:34816
	ds_read_b128 v[194:197], v246 offset:34816
	ds_read_b128 v[198:201], v153 offset:36864
	ds_read_b128 v[202:205], v246 offset:36864
	ds_read_b128 v[206:209], v153 offset:38912
	ds_read_b128 v[210:213], v246 offset:38912
	global_load_lds_dwordx4 v[222:223], off
	v_lshl_add_u64 v[222:223], s[28:29], 0, v[130:131]
	s_mov_b32 m0, s36
	s_nop 0
	global_load_lds_dwordx4 v[222:223], off
	s_waitcnt vmcnt(8)
	s_waitcnt lgkmcnt(0)
	s_barrier
	s_waitcnt lgkmcnt(0)
	v_mfma_f32_16x16x32_bf16 v[124:127], v[144:147], v[182:185], v[124:127]
	v_mfma_f32_16x16x32_bf16 v[120:123], v[158:161], v[182:185], v[120:123]
	v_mfma_f32_16x16x32_bf16 v[108:111], v[144:147], v[190:193], v[108:111]
	v_mfma_f32_16x16x32_bf16 v[104:107], v[158:161], v[190:193], v[104:107]
	v_mfma_f32_16x16x32_bf16 v[92:95], v[144:147], v[198:201], v[92:95]
	v_mfma_f32_16x16x32_bf16 v[88:91], v[158:161], v[198:201], v[88:91]
	v_mfma_f32_16x16x32_bf16 v[76:79], v[144:147], v[206:209], v[76:79]
	v_mfma_f32_16x16x32_bf16 v[72:75], v[158:161], v[206:209], v[72:75]
	v_mfma_f32_16x16x32_bf16 v[124:127], v[154:157], v[186:189], v[124:127]
	v_mfma_f32_16x16x32_bf16 v[120:123], v[162:165], v[186:189], v[120:123]
	v_mfma_f32_16x16x32_bf16 v[108:111], v[154:157], v[194:197], v[108:111]
	v_mfma_f32_16x16x32_bf16 v[104:107], v[162:165], v[194:197], v[104:107]
	v_mfma_f32_16x16x32_bf16 v[92:95], v[154:157], v[202:205], v[92:95]
	v_mfma_f32_16x16x32_bf16 v[88:91], v[162:165], v[202:205], v[88:91]
	v_mfma_f32_16x16x32_bf16 v[76:79], v[154:157], v[210:213], v[76:79]
	v_mfma_f32_16x16x32_bf16 v[72:75], v[162:165], v[210:213], v[72:75]
	v_mfma_f32_16x16x32_bf16 v[116:119], v[166:169], v[182:185], v[116:119]
	v_mfma_f32_16x16x32_bf16 v[112:115], v[174:177], v[182:185], v[112:115]
	v_mfma_f32_16x16x32_bf16 v[100:103], v[166:169], v[190:193], v[100:103]
	v_mfma_f32_16x16x32_bf16 v[96:99], v[174:177], v[190:193], v[96:99]
	v_mfma_f32_16x16x32_bf16 v[84:87], v[166:169], v[198:201], v[84:87]
	v_mfma_f32_16x16x32_bf16 v[80:83], v[174:177], v[198:201], v[80:83]
	v_mfma_f32_16x16x32_bf16 v[68:71], v[166:169], v[206:209], v[68:71]
	v_mfma_f32_16x16x32_bf16 v[64:67], v[174:177], v[206:209], v[64:67]
	v_mfma_f32_16x16x32_bf16 v[116:119], v[170:173], v[186:189], v[116:119]
	v_mfma_f32_16x16x32_bf16 v[112:115], v[178:181], v[186:189], v[112:115]
	v_mfma_f32_16x16x32_bf16 v[100:103], v[170:173], v[194:197], v[100:103]
	v_mfma_f32_16x16x32_bf16 v[96:99], v[178:181], v[194:197], v[96:99]
	v_mfma_f32_16x16x32_bf16 v[84:87], v[170:173], v[202:205], v[84:87]
	v_mfma_f32_16x16x32_bf16 v[80:83], v[178:181], v[202:205], v[80:83]
	v_mfma_f32_16x16x32_bf16 v[68:71], v[170:173], v[210:213], v[68:71]
	v_mfma_f32_16x16x32_bf16 v[64:67], v[178:181], v[210:213], v[64:67]
	s_barrier
	s_add_i32 s28, s51, s30
	v_lshl_add_u64 v[214:215], v[214:215], 0, s[10:11]
	s_mov_b32 m0, s28
	ds_read_b128 v[182:185], v153 offset:49152
	ds_read_b128 v[186:189], v246 offset:49152
	ds_read_b128 v[190:193], v153 offset:51200
	ds_read_b128 v[194:197], v246 offset:51200
	ds_read_b128 v[198:201], v153 offset:53248
	ds_read_b128 v[202:205], v246 offset:53248
	ds_read_b128 v[206:209], v153 offset:55296
	ds_read_b128 v[210:213], v246 offset:55296
	global_load_lds_dwordx4 v[214:215], off
	s_add_i32 m0, s28, 0x2000
	s_add_u32 s26, s26, 0x40080
	v_lshl_add_u64 v[214:215], v[216:217], 0, s[10:11]
	s_addc_u32 s27, s27, 0
	s_add_i32 s28, s52, s30
	global_load_lds_dwordx4 v[214:215], off
	v_lshl_add_u64 v[214:215], s[26:27], 0, v[132:133]
	s_mov_b32 m0, s28
	s_nop 0
	global_load_lds_dwordx4 v[214:215], off
	v_lshl_add_u64 v[214:215], s[26:27], 0, v[128:129]
	s_add_i32 m0, s28, 0x2000
	s_nop 0
	global_load_lds_dwordx4 v[214:215], off
	v_lshl_add_u64 v[214:215], v[218:219], 0, s[10:11]
	s_mov_b32 m0, s39
	s_nop 0
	global_load_lds_dwordx4 v[214:215], off
	v_lshl_add_u64 v[214:215], v[220:221], 0, s[10:11]
	s_mov_b32 m0, s40
	s_nop 0
	global_load_lds_dwordx4 v[214:215], off
	s_waitcnt vmcnt(8)
	s_waitcnt lgkmcnt(0)
	s_barrier
	s_waitcnt lgkmcnt(0)
	v_mfma_f32_16x16x32_bf16 v[60:63], v[144:147], v[182:185], v[60:63]
	v_mfma_f32_16x16x32_bf16 v[56:59], v[158:161], v[182:185], v[56:59]
	v_mfma_f32_16x16x32_bf16 v[44:47], v[144:147], v[190:193], v[44:47]
	v_mfma_f32_16x16x32_bf16 v[40:43], v[158:161], v[190:193], v[40:43]
	v_mfma_f32_16x16x32_bf16 v[28:31], v[144:147], v[198:201], v[28:31]
	v_mfma_f32_16x16x32_bf16 v[24:27], v[158:161], v[198:201], v[24:27]
	v_mfma_f32_16x16x32_bf16 v[12:15], v[144:147], v[206:209], v[12:15]
	v_mfma_f32_16x16x32_bf16 v[8:11], v[158:161], v[206:209], v[8:11]
	v_mfma_f32_16x16x32_bf16 v[60:63], v[154:157], v[186:189], v[60:63]
	v_mfma_f32_16x16x32_bf16 v[56:59], v[162:165], v[186:189], v[56:59]
	v_mfma_f32_16x16x32_bf16 v[44:47], v[154:157], v[194:197], v[44:47]
	v_mfma_f32_16x16x32_bf16 v[40:43], v[162:165], v[194:197], v[40:43]
	v_mfma_f32_16x16x32_bf16 v[28:31], v[154:157], v[202:205], v[28:31]
	v_mfma_f32_16x16x32_bf16 v[24:27], v[162:165], v[202:205], v[24:27]
	v_mfma_f32_16x16x32_bf16 v[12:15], v[154:157], v[210:213], v[12:15]
	v_mfma_f32_16x16x32_bf16 v[8:11], v[162:165], v[210:213], v[8:11]
	v_mfma_f32_16x16x32_bf16 v[52:55], v[166:169], v[182:185], v[52:55]
	v_mfma_f32_16x16x32_bf16 v[48:51], v[174:177], v[182:185], v[48:51]
	v_mfma_f32_16x16x32_bf16 v[36:39], v[166:169], v[190:193], v[36:39]
	v_mfma_f32_16x16x32_bf16 v[32:35], v[174:177], v[190:193], v[32:35]
	v_mfma_f32_16x16x32_bf16 v[20:23], v[166:169], v[198:201], v[20:23]
	v_mfma_f32_16x16x32_bf16 v[16:19], v[174:177], v[198:201], v[16:19]
	v_mfma_f32_16x16x32_bf16 v[4:7], v[166:169], v[206:209], v[4:7]
	v_mfma_f32_16x16x32_bf16 v[0:3], v[174:177], v[206:209], v[0:3]
	v_mfma_f32_16x16x32_bf16 v[52:55], v[170:173], v[186:189], v[52:55]
	v_mfma_f32_16x16x32_bf16 v[48:51], v[178:181], v[186:189], v[48:51]
	v_mfma_f32_16x16x32_bf16 v[36:39], v[170:173], v[194:197], v[36:39]
	v_mfma_f32_16x16x32_bf16 v[32:35], v[178:181], v[194:197], v[32:35]
	v_mfma_f32_16x16x32_bf16 v[20:23], v[170:173], v[202:205], v[20:23]
	v_mfma_f32_16x16x32_bf16 v[16:19], v[178:181], v[202:205], v[16:19]
	v_mfma_f32_16x16x32_bf16 v[4:7], v[170:173], v[210:213], v[4:7]
	v_mfma_f32_16x16x32_bf16 v[0:3], v[178:181], v[210:213], v[0:3]
	s_barrier
	s_add_i32 s50, s50, 2
	s_add_u32 s24, s24, 0x100
	s_addc_u32 s25, s25, 0
	s_add_u32 s48, s48, 0x100
	s_addc_u32 s49, s49, 0
	s_cmp_gt_u32 s50, 13
	.p2align 6

.LBB0_295:
	s_add_u32 s46, s20, 0x100
	s_addc_u32 s47, s21, 0
	s_mov_b32 s48, -2
	s_waitcnt lgkmcnt(0)
	v_xor_b32_e32 v246, 64, v171
	v_xor_b32_e32 v247, 64, v167
	v_add_u32_e32 v248, s40, v247
	v_add_u32_e32 v249, s41, v247
	ds_read_b128 v[144:147], v169
	ds_read_b128 v[148:151], v248
	ds_read_b128 v[152:155], v169 offset:2048
	ds_read_b128 v[156:159], v248 offset:2048
	ds_read_b128 v[160:163], v170
	ds_read_b128 v[172:175], v249
	ds_read_b128 v[176:179], v170 offset:2048
	ds_read_b128 v[180:183], v249 offset:2048
	s_add_u32 s20, s18, 0x100
	s_addc_u32 s21, s19, 0
	s_cmp_eq_u32 s48, 40
	s_cselect_b32 s25, s9, s21
	s_cselect_b32 s24, s8, s20
	s_cselect_b32 s23, s17, s47
	s_cselect_b32 s22, s16, s46
	v_lshl_add_u64 v[164:165], s[18:19], 0, v[136:137]
	s_add_i32 m0, s28, 0xc000
	ds_read_b128 v[184:187], v171
	ds_read_b128 v[188:191], v246
	ds_read_b128 v[192:195], v171 offset:2048
	ds_read_b128 v[196:199], v246 offset:2048
	ds_read_b128 v[200:203], v171 offset:4096
	ds_read_b128 v[204:207], v246 offset:4096
	ds_read_b128 v[208:211], v171 offset:6144
	ds_read_b128 v[212:215], v246 offset:6144
	global_load_lds_dwordx4 v[164:165], off
	v_lshl_add_u64 v[164:165], s[18:19], 0, v[138:139]
	s_add_i32 m0, s28, 0xe000
	s_nop 0
	global_load_lds_dwordx4 v[164:165], off
	s_waitcnt vmcnt(8)
	s_waitcnt lgkmcnt(0)
	s_barrier
	s_waitcnt lgkmcnt(0)
	v_mfma_f32_16x16x32_bf16 v[124:127], v[144:147], v[184:187], 0
	v_mfma_f32_16x16x32_bf16 v[120:123], v[152:155], v[184:187], 0
	v_mfma_f32_16x16x32_bf16 v[116:119], v[144:147], v[192:195], 0
	v_mfma_f32_16x16x32_bf16 v[112:115], v[152:155], v[192:195], 0
	v_mfma_f32_16x16x32_bf16 v[96:99], v[144:147], v[200:203], 0
	v_mfma_f32_16x16x32_bf16 v[88:91], v[152:155], v[200:203], 0
	v_mfma_f32_16x16x32_bf16 v[80:83], v[144:147], v[208:211], 0
	v_mfma_f32_16x16x32_bf16 v[72:75], v[152:155], v[208:211], 0
	v_mfma_f32_16x16x32_bf16 v[124:127], v[148:151], v[188:191], v[124:127]
	v_mfma_f32_16x16x32_bf16 v[120:123], v[156:159], v[188:191], v[120:123]
	v_mfma_f32_16x16x32_bf16 v[116:119], v[148:151], v[196:199], v[116:119]
	v_mfma_f32_16x16x32_bf16 v[112:115], v[156:159], v[196:199], v[112:115]
	v_mfma_f32_16x16x32_bf16 v[96:99], v[148:151], v[204:207], v[96:99]
	v_mfma_f32_16x16x32_bf16 v[88:91], v[156:159], v[204:207], v[88:91]
	v_mfma_f32_16x16x32_bf16 v[80:83], v[148:151], v[212:215], v[80:83]
	v_mfma_f32_16x16x32_bf16 v[72:75], v[156:159], v[212:215], v[72:75]
	v_mfma_f32_16x16x32_bf16 v[108:111], v[160:163], v[184:187], 0
	v_mfma_f32_16x16x32_bf16 v[104:107], v[176:179], v[184:187], 0
	v_mfma_f32_16x16x32_bf16 v[100:103], v[160:163], v[192:195], 0
	v_mfma_f32_16x16x32_bf16 v[92:95], v[176:179], v[192:195], 0
	v_mfma_f32_16x16x32_bf16 v[84:87], v[160:163], v[200:203], 0
	v_mfma_f32_16x16x32_bf16 v[76:79], v[176:179], v[200:203], 0
	v_mfma_f32_16x16x32_bf16 v[68:71], v[160:163], v[208:211], 0
	v_mfma_f32_16x16x32_bf16 v[64:67], v[176:179], v[208:211], 0
	v_mfma_f32_16x16x32_bf16 v[108:111], v[172:175], v[188:191], v[108:111]
	v_mfma_f32_16x16x32_bf16 v[104:107], v[180:183], v[188:191], v[104:107]
	v_mfma_f32_16x16x32_bf16 v[100:103], v[172:175], v[196:199], v[100:103]
	v_mfma_f32_16x16x32_bf16 v[92:95], v[180:183], v[196:199], v[92:95]
	v_mfma_f32_16x16x32_bf16 v[84:87], v[172:175], v[204:207], v[84:87]
	v_mfma_f32_16x16x32_bf16 v[76:79], v[180:183], v[204:207], v[76:79]
	v_mfma_f32_16x16x32_bf16 v[68:71], v[172:175], v[212:215], v[68:71]
	v_mfma_f32_16x16x32_bf16 v[64:67], v[180:183], v[212:215], v[64:67]
	s_barrier
	s_add_i32 s18, s40, s26
	v_lshl_add_u64 v[164:165], s[22:23], 0, v[132:133]
	s_mov_b32 m0, s18
	ds_read_b128 v[184:187], v171 offset:16384
	ds_read_b128 v[188:191], v246 offset:16384
	ds_read_b128 v[192:195], v171 offset:18432
	ds_read_b128 v[196:199], v246 offset:18432
	ds_read_b128 v[200:203], v171 offset:20480
	ds_read_b128 v[204:207], v246 offset:20480
	ds_read_b128 v[208:211], v171 offset:22528
	ds_read_b128 v[212:215], v246 offset:22528
	global_load_lds_dwordx4 v[164:165], off
	s_add_i32 m0, s18, 0x2000
	s_add_u32 s18, s22, 0xb0000
	v_lshl_add_u64 v[216:217], s[22:23], 0, v[128:129]
	s_addc_u32 s19, s23, 0
	s_add_i32 s49, s41, s26
	global_load_lds_dwordx4 v[216:217], off
	v_lshl_add_u64 v[218:219], s[18:19], 0, v[132:133]
	s_mov_b32 m0, s49
	v_lshl_add_u64 v[220:221], s[24:25], 0, v[130:131]
	global_load_lds_dwordx4 v[218:219], off
	v_lshl_add_u64 v[218:219], s[18:19], 0, v[128:129]
	s_add_i32 m0, s49, 0x2000
	s_nop 0
	global_load_lds_dwordx4 v[218:219], off
	v_lshl_add_u64 v[218:219], s[24:25], 0, v[134:135]
	s_mov_b32 m0, s28
	s_nop 0
	global_load_lds_dwordx4 v[218:219], off
	s_mov_b32 m0, s29
	s_nop 0
	global_load_lds_dwordx4 v[220:221], off
	s_waitcnt vmcnt(8)
	s_waitcnt lgkmcnt(0)
	s_barrier
	s_waitcnt lgkmcnt(0)
	v_mfma_f32_16x16x32_bf16 v[60:63], v[144:147], v[184:187], 0
	v_mfma_f32_16x16x32_bf16 v[56:59], v[152:155], v[184:187], 0
	v_mfma_f32_16x16x32_bf16 v[48:51], v[144:147], v[192:195], 0
	v_mfma_f32_16x16x32_bf16 v[40:43], v[152:155], v[192:195], 0
	v_mfma_f32_16x16x32_bf16 v[32:35], v[144:147], v[200:203], 0
	v_mfma_f32_16x16x32_bf16 v[24:27], v[152:155], v[200:203], 0
	v_mfma_f32_16x16x32_bf16 v[16:19], v[144:147], v[208:211], 0
	v_mfma_f32_16x16x32_bf16 v[8:11], v[152:155], v[208:211], 0
	v_mfma_f32_16x16x32_bf16 v[60:63], v[148:151], v[188:191], v[60:63]
	v_mfma_f32_16x16x32_bf16 v[56:59], v[156:159], v[188:191], v[56:59]
	v_mfma_f32_16x16x32_bf16 v[48:51], v[148:151], v[196:199], v[48:51]
	v_mfma_f32_16x16x32_bf16 v[40:43], v[156:159], v[196:199], v[40:43]
	v_mfma_f32_16x16x32_bf16 v[32:35], v[148:151], v[204:207], v[32:35]
	v_mfma_f32_16x16x32_bf16 v[24:27], v[156:159], v[204:207], v[24:27]
	v_mfma_f32_16x16x32_bf16 v[16:19], v[148:151], v[212:215], v[16:19]
	v_mfma_f32_16x16x32_bf16 v[8:11], v[156:159], v[212:215], v[8:11]
	v_mfma_f32_16x16x32_bf16 v[52:55], v[160:163], v[184:187], 0
	v_mfma_f32_16x16x32_bf16 v[44:47], v[176:179], v[184:187], 0
	v_mfma_f32_16x16x32_bf16 v[36:39], v[160:163], v[192:195], 0
	v_mfma_f32_16x16x32_bf16 v[28:31], v[176:179], v[192:195], 0
	v_mfma_f32_16x16x32_bf16 v[20:23], v[160:163], v[200:203], 0
	v_mfma_f32_16x16x32_bf16 v[12:15], v[176:179], v[200:203], 0
	v_mfma_f32_16x16x32_bf16 v[4:7], v[160:163], v[208:211], 0
	v_mfma_f32_16x16x32_bf16 v[0:3], v[176:179], v[208:211], 0
	v_mfma_f32_16x16x32_bf16 v[52:55], v[172:175], v[188:191], v[52:55]
	v_mfma_f32_16x16x32_bf16 v[44:47], v[180:183], v[188:191], v[44:47]
	v_mfma_f32_16x16x32_bf16 v[36:39], v[172:175], v[196:199], v[36:39]
	v_mfma_f32_16x16x32_bf16 v[28:31], v[180:183], v[196:199], v[28:31]
	v_mfma_f32_16x16x32_bf16 v[20:23], v[172:175], v[204:207], v[20:23]
	v_mfma_f32_16x16x32_bf16 v[12:15], v[180:183], v[204:207], v[12:15]
	v_mfma_f32_16x16x32_bf16 v[4:7], v[172:175], v[212:215], v[4:7]
	v_mfma_f32_16x16x32_bf16 v[0:3], v[180:183], v[212:215], v[0:3]
	s_barrier
	s_add_i32 s49, 0, 0x18000
	s_add_i32 s50, 0, 0x1c000
	v_add_u32_e32 v156, s49, v167
	v_add_u32_e32 v250, s49, v247
	v_add_u32_e32 v180, s50, v167
	v_add_u32_e32 v251, s50, v247
	ds_read_b128 v[144:147], v156
	ds_read_b128 v[148:151], v250
	ds_read_b128 v[152:155], v156 offset:2048
	ds_read_b128 v[156:159], v250 offset:2048
	ds_read_b128 v[160:163], v180
	ds_read_b128 v[172:175], v251
	ds_read_b128 v[176:179], v180 offset:2048
	ds_read_b128 v[180:183], v251 offset:2048
	s_add_u32 s18, s24, 0xb0000
	s_addc_u32 s19, s25, 0
	s_mov_b32 m0, s30
	v_lshl_add_u64 v[222:223], s[18:19], 0, v[134:135]
	ds_read_b128 v[184:187], v171 offset:32768
	ds_read_b128 v[188:191], v246 offset:32768
	ds_read_b128 v[192:195], v171 offset:34816
	ds_read_b128 v[196:199], v246 offset:34816
	ds_read_b128 v[200:203], v171 offset:36864
	ds_read_b128 v[204:207], v246 offset:36864
	ds_read_b128 v[208:211], v171 offset:38912
	ds_read_b128 v[212:215], v246 offset:38912
	global_load_lds_dwordx4 v[222:223], off
	v_lshl_add_u64 v[222:223], s[18:19], 0, v[130:131]
	s_mov_b32 m0, s31
	s_nop 0
	global_load_lds_dwordx4 v[222:223], off
	s_waitcnt vmcnt(8)
	s_waitcnt lgkmcnt(0)
	s_barrier
	s_waitcnt lgkmcnt(0)
	v_mfma_f32_16x16x32_bf16 v[124:127], v[144:147], v[184:187], v[124:127]
	v_mfma_f32_16x16x32_bf16 v[120:123], v[152:155], v[184:187], v[120:123]
	v_mfma_f32_16x16x32_bf16 v[116:119], v[144:147], v[192:195], v[116:119]
	v_mfma_f32_16x16x32_bf16 v[112:115], v[152:155], v[192:195], v[112:115]
	v_mfma_f32_16x16x32_bf16 v[96:99], v[144:147], v[200:203], v[96:99]
	v_mfma_f32_16x16x32_bf16 v[88:91], v[152:155], v[200:203], v[88:91]
	v_mfma_f32_16x16x32_bf16 v[80:83], v[144:147], v[208:211], v[80:83]
	v_mfma_f32_16x16x32_bf16 v[72:75], v[152:155], v[208:211], v[72:75]
	v_mfma_f32_16x16x32_bf16 v[124:127], v[148:151], v[188:191], v[124:127]
	v_mfma_f32_16x16x32_bf16 v[120:123], v[156:159], v[188:191], v[120:123]
	v_mfma_f32_16x16x32_bf16 v[116:119], v[148:151], v[196:199], v[116:119]
	v_mfma_f32_16x16x32_bf16 v[112:115], v[156:159], v[196:199], v[112:115]
	v_mfma_f32_16x16x32_bf16 v[96:99], v[148:151], v[204:207], v[96:99]
	v_mfma_f32_16x16x32_bf16 v[88:91], v[156:159], v[204:207], v[88:91]
	v_mfma_f32_16x16x32_bf16 v[80:83], v[148:151], v[212:215], v[80:83]
	v_mfma_f32_16x16x32_bf16 v[72:75], v[156:159], v[212:215], v[72:75]
	v_mfma_f32_16x16x32_bf16 v[108:111], v[160:163], v[184:187], v[108:111]
	v_mfma_f32_16x16x32_bf16 v[104:107], v[176:179], v[184:187], v[104:107]
	v_mfma_f32_16x16x32_bf16 v[100:103], v[160:163], v[192:195], v[100:103]
	v_mfma_f32_16x16x32_bf16 v[92:95], v[176:179], v[192:195], v[92:95]
	v_mfma_f32_16x16x32_bf16 v[84:87], v[160:163], v[200:203], v[84:87]
	v_mfma_f32_16x16x32_bf16 v[76:79], v[176:179], v[200:203], v[76:79]
	v_mfma_f32_16x16x32_bf16 v[68:71], v[160:163], v[208:211], v[68:71]
	v_mfma_f32_16x16x32_bf16 v[64:67], v[176:179], v[208:211], v[64:67]
	v_mfma_f32_16x16x32_bf16 v[108:111], v[172:175], v[188:191], v[108:111]
	v_mfma_f32_16x16x32_bf16 v[104:107], v[180:183], v[188:191], v[104:107]
	v_mfma_f32_16x16x32_bf16 v[100:103], v[172:175], v[196:199], v[100:103]
	v_mfma_f32_16x16x32_bf16 v[92:95], v[180:183], v[196:199], v[92:95]
	v_mfma_f32_16x16x32_bf16 v[84:87], v[172:175], v[204:207], v[84:87]
	v_mfma_f32_16x16x32_bf16 v[76:79], v[180:183], v[204:207], v[76:79]
	v_mfma_f32_16x16x32_bf16 v[68:71], v[172:175], v[212:215], v[68:71]
	v_mfma_f32_16x16x32_bf16 v[64:67], v[180:183], v[212:215], v[64:67]
	s_barrier
	s_add_i32 s18, s49, s26
	v_lshl_add_u64 v[164:165], v[164:165], 0, s[12:13]
	s_mov_b32 m0, s18
	ds_read_b128 v[184:187], v171 offset:49152
	ds_read_b128 v[188:191], v246 offset:49152
	ds_read_b128 v[192:195], v171 offset:51200
	ds_read_b128 v[196:199], v246 offset:51200
	ds_read_b128 v[200:203], v171 offset:53248
	ds_read_b128 v[204:207], v246 offset:53248
	ds_read_b128 v[208:211], v171 offset:55296
	ds_read_b128 v[212:215], v246 offset:55296
	global_load_lds_dwordx4 v[164:165], off
	s_add_i32 m0, s18, 0x2000
	s_add_u32 s18, s22, 0xb0080
	v_lshl_add_u64 v[164:165], v[216:217], 0, s[12:13]
	s_addc_u32 s19, s23, 0
	s_add_i32 s22, s50, s26
	global_load_lds_dwordx4 v[164:165], off
	v_lshl_add_u64 v[164:165], s[18:19], 0, v[132:133]
	s_mov_b32 m0, s22
	s_nop 0
	global_load_lds_dwordx4 v[164:165], off
	v_lshl_add_u64 v[164:165], s[18:19], 0, v[128:129]
	s_add_i32 m0, s22, 0x2000
	s_nop 0
	global_load_lds_dwordx4 v[164:165], off
	v_lshl_add_u64 v[164:165], v[218:219], 0, s[12:13]
	s_mov_b32 m0, s37
	s_nop 0
	global_load_lds_dwordx4 v[164:165], off
	v_lshl_add_u64 v[164:165], v[220:221], 0, s[12:13]
	s_mov_b32 m0, s38
	s_nop 0
	global_load_lds_dwordx4 v[164:165], off
	s_waitcnt vmcnt(8)
	s_waitcnt lgkmcnt(0)
	s_barrier
	s_waitcnt lgkmcnt(0)
	v_mfma_f32_16x16x32_bf16 v[60:63], v[144:147], v[184:187], v[60:63]
	v_mfma_f32_16x16x32_bf16 v[56:59], v[152:155], v[184:187], v[56:59]
	v_mfma_f32_16x16x32_bf16 v[48:51], v[144:147], v[192:195], v[48:51]
	v_mfma_f32_16x16x32_bf16 v[40:43], v[152:155], v[192:195], v[40:43]
	v_mfma_f32_16x16x32_bf16 v[32:35], v[144:147], v[200:203], v[32:35]
	v_mfma_f32_16x16x32_bf16 v[24:27], v[152:155], v[200:203], v[24:27]
	v_mfma_f32_16x16x32_bf16 v[16:19], v[144:147], v[208:211], v[16:19]
	v_mfma_f32_16x16x32_bf16 v[8:11], v[152:155], v[208:211], v[8:11]
	v_mfma_f32_16x16x32_bf16 v[60:63], v[148:151], v[188:191], v[60:63]
	v_mfma_f32_16x16x32_bf16 v[56:59], v[156:159], v[188:191], v[56:59]
	v_mfma_f32_16x16x32_bf16 v[48:51], v[148:151], v[196:199], v[48:51]
	v_mfma_f32_16x16x32_bf16 v[40:43], v[156:159], v[196:199], v[40:43]
	v_mfma_f32_16x16x32_bf16 v[32:35], v[148:151], v[204:207], v[32:35]
	v_mfma_f32_16x16x32_bf16 v[24:27], v[156:159], v[204:207], v[24:27]
	v_mfma_f32_16x16x32_bf16 v[16:19], v[148:151], v[212:215], v[16:19]
	v_mfma_f32_16x16x32_bf16 v[8:11], v[156:159], v[212:215], v[8:11]
	v_mfma_f32_16x16x32_bf16 v[52:55], v[160:163], v[184:187], v[52:55]
	v_mfma_f32_16x16x32_bf16 v[44:47], v[176:179], v[184:187], v[44:47]
	v_mfma_f32_16x16x32_bf16 v[36:39], v[160:163], v[192:195], v[36:39]
	v_mfma_f32_16x16x32_bf16 v[28:31], v[176:179], v[192:195], v[28:31]
	v_mfma_f32_16x16x32_bf16 v[20:23], v[160:163], v[200:203], v[20:23]
	v_mfma_f32_16x16x32_bf16 v[12:15], v[176:179], v[200:203], v[12:15]
	v_mfma_f32_16x16x32_bf16 v[4:7], v[160:163], v[208:211], v[4:7]
	v_mfma_f32_16x16x32_bf16 v[0:3], v[176:179], v[208:211], v[0:3]
	v_mfma_f32_16x16x32_bf16 v[52:55], v[172:175], v[188:191], v[52:55]
	v_mfma_f32_16x16x32_bf16 v[44:47], v[180:183], v[188:191], v[44:47]
	v_mfma_f32_16x16x32_bf16 v[36:39], v[172:175], v[196:199], v[36:39]
	v_mfma_f32_16x16x32_bf16 v[28:31], v[180:183], v[196:199], v[28:31]
	v_mfma_f32_16x16x32_bf16 v[20:23], v[172:175], v[204:207], v[20:23]
	v_mfma_f32_16x16x32_bf16 v[12:15], v[180:183], v[204:207], v[12:15]
	v_mfma_f32_16x16x32_bf16 v[4:7], v[172:175], v[212:215], v[4:7]
	v_mfma_f32_16x16x32_bf16 v[0:3], v[180:183], v[212:215], v[0:3]
	s_barrier
	s_add_i32 s48, s48, 2
	s_add_u32 s46, s46, 0x100
	s_addc_u32 s47, s47, 0
	s_cmp_gt_u32 s48, 41
	s_mov_b64 s[18:19], s[20:21]
	.p2align 6

.LBB0_430:
	s_add_u32 s28, s28, 0x40080
	s_addc_u32 s29, s29, 0
	s_add_u32 s56, s30, 0x100
	s_addc_u32 s57, s31, 0
	s_mov_b32 s58, -2
	v_xor_b32_e32 v246, 64, v241
	v_xor_b32_e32 v247, 64, v237
	v_add_u32_e32 v248, s50, v247
	v_add_u32_e32 v249, s51, v247
	ds_read_b128 v[130:133], v239
	ds_read_b128 v[134:137], v248
	ds_read_b128 v[138:141], v239 offset:2048
	ds_read_b128 v[142:145], v248 offset:2048
	ds_read_b128 v[146:149], v240
	ds_read_b128 v[150:153], v249
	ds_read_b128 v[154:157], v240 offset:2048
	ds_read_b128 v[158:161], v249 offset:2048
	s_add_u32 s30, s28, 0xfffc0080
	s_addc_u32 s31, s29, -1
	s_cmp_eq_u32 s58, 12
	s_cselect_b32 s35, s9, s31
	s_cselect_b32 s34, s23, s30
	s_cselect_b32 s31, s21, s57
	s_cselect_b32 s30, s55, s56
	v_lshl_add_u64 v[80:81], s[28:29], 0, v[222:223]
	s_add_i32 m0, s36, 0xc000
	ds_read_b128 v[162:165], v241
	ds_read_b128 v[166:169], v246
	ds_read_b128 v[170:173], v241 offset:2048
	ds_read_b128 v[174:177], v246 offset:2048
	ds_read_b128 v[178:181], v241 offset:4096
	ds_read_b128 v[182:185], v246 offset:4096
	ds_read_b128 v[186:189], v241 offset:6144
	ds_read_b128 v[190:193], v246 offset:6144
	global_load_lds_dwordx4 v[80:81], off
	v_lshl_add_u64 v[80:81], s[28:29], 0, v[224:225]
	s_add_i32 m0, s36, 0xe000
	s_nop 0
	global_load_lds_dwordx4 v[80:81], off
	s_waitcnt vmcnt(8)
	s_waitcnt lgkmcnt(0)
	s_barrier
	s_waitcnt lgkmcnt(0)
	v_mfma_f32_16x16x32_bf16 v[126:129], v[130:133], v[162:165], 0
	s_add_i32 s54, s54, 1
	s_mul_i32 s6, s54, s44
	s_mul_hi_u32 s7, s54, s49
	v_mfma_f32_16x16x32_bf16 v[122:125], v[138:141], v[162:165], 0
	s_add_i32 s7, s7, s6
	s_mul_i32 s6, s54, s49
	s_add_u32 s24, s6, s96
	v_mfma_f32_16x16x32_bf16 v[110:113], v[130:133], v[170:173], 0
	s_addc_u32 s25, s7, s45
	v_cmp_lt_i64_e64 s[6:7], s[24:25], v[226:227]
	s_ashr_i32 s9, s24, 31
	v_mfma_f32_16x16x32_bf16 v[106:109], v[138:141], v[170:173], 0
	s_lshr_b32 s9, s9, 29
	s_add_i32 s9, s24, s9
	s_ashr_i32 s20, s9, 3
	v_mfma_f32_16x16x32_bf16 v[94:97], v[130:133], v[178:181], 0
	s_and_b32 s9, s9, -8
	s_sub_i32 s9, s24, s9
	s_cmp_lt_i32 s9, 0
	v_mfma_f32_16x16x32_bf16 v[90:93], v[138:141], v[178:181], 0
	s_movk_i32 s21, 0xe1
	s_cselect_b32 s21, s21, 0xe0
	s_mul_i32 s9, s9, s21
	v_mfma_f32_16x16x32_bf16 v[76:79], v[130:133], v[186:189], 0
	s_add_i32 s9, s9, s20
	s_mul_hi_i32 s20, s9, 0x92492493
	s_add_i32 s20, s20, s9
	v_mfma_f32_16x16x32_bf16 v[72:75], v[138:141], v[186:189], 0
	s_lshr_b32 s21, s20, 31
	s_ashr_i32 s20, s20, 6
	s_add_i32 s20, s20, s21
	v_mfma_f32_16x16x32_bf16 v[126:129], v[134:137], v[166:169], v[126:129]
	s_lshl_b32 s21, s20, 3
	s_sub_i32 s22, 0x80, s21
	s_min_i32 s22, s22, 8
	v_mfma_f32_16x16x32_bf16 v[122:125], v[142:145], v[166:169], v[122:125]
	s_abs_i32 s23, s22
	v_cvt_f32_u32_e32 v252, s23
	s_sub_i32 s25, 0, s23
	v_mfma_f32_16x16x32_bf16 v[110:113], v[134:137], v[174:177], v[110:113]
	s_mulk_i32 s20, 0x70
	s_sub_i32 s9, s9, s20
	v_rcp_iflag_f32_e32 v252, v252
	v_mfma_f32_16x16x32_bf16 v[106:109], v[142:145], v[174:177], v[106:109]
	s_abs_i32 s20, s9
	s_xor_b32 s24, s9, s22
	s_ashr_i32 s24, s24, 31
	v_mfma_f32_16x16x32_bf16 v[94:97], v[134:137], v[182:185], v[94:97]
	v_mul_f32_e32 v252, 0x4f7ffffe, v252
	v_cvt_u32_f32_e32 v252, v252
	s_nop 0
	v_mfma_f32_16x16x32_bf16 v[90:93], v[142:145], v[182:185], v[90:93]
	v_readfirstlane_b32 s26, v252
	s_mul_i32 s25, s25, s26
	s_mul_hi_u32 s25, s26, s25
	v_mfma_f32_16x16x32_bf16 v[76:79], v[134:137], v[190:193], v[76:79]
	s_add_i32 s26, s26, s25
	s_mul_hi_u32 s25, s20, s26
	s_mul_i32 s26, s25, s23
	v_mfma_f32_16x16x32_bf16 v[72:75], v[142:145], v[190:193], v[72:75]
	s_sub_i32 s20, s20, s26
	s_add_i32 s27, s25, 1
	s_sub_i32 s26, s20, s23
	v_mfma_f32_16x16x32_bf16 v[118:121], v[146:149], v[162:165], 0
	s_cmp_ge_u32 s20, s23
	s_cselect_b32 s25, s27, s25
	s_cselect_b32 s20, s26, s20
	v_mfma_f32_16x16x32_bf16 v[114:117], v[154:157], v[162:165], 0
	s_add_i32 s26, s25, 1
	s_cmp_ge_u32 s20, s23
	s_cselect_b32 s20, s26, s25
	v_mfma_f32_16x16x32_bf16 v[102:105], v[146:149], v[170:173], 0
	s_xor_b32 s20, s20, s24
	s_sub_i32 s20, s20, s24
	s_mul_i32 s22, s20, s22
	v_mfma_f32_16x16x32_bf16 v[98:101], v[154:157], v[170:173], 0
	s_sub_i32 s9, s9, s22
	s_add_i32 s22, s21, s9
	s_ashr_i32 s23, s22, 31
	v_mfma_f32_16x16x32_bf16 v[86:89], v[146:149], v[178:181], 0
	s_lshl_b64 s[24:25], s[22:23], 19
	s_add_u32 s24, s90, s24
	s_addc_u32 s25, s91, s25
	v_mfma_f32_16x16x32_bf16 v[80:83], v[154:157], v[178:181], 0
	s_and_b64 s[26:27], s[6:7], exec
	s_cselect_b32 s9, s25, s29
	s_cselect_b32 s23, s24, s28
	v_mfma_f32_16x16x32_bf16 v[68:71], v[146:149], v[186:189], 0
	s_ashr_i32 s21, s20, 31
	s_lshl_b64 s[26:27], s[20:21], 19
	s_add_u32 s26, s2, s26
	v_mfma_f32_16x16x32_bf16 v[64:67], v[154:157], v[186:189], 0
	s_addc_u32 s27, s3, s27
	s_and_b64 s[98:99], s[6:7], exec
	s_cselect_b32 s21, s27, s31
	v_mfma_f32_16x16x32_bf16 v[118:121], v[150:153], v[166:169], v[118:121]
	s_cselect_b32 s55, s26, s30
	v_mfma_f32_16x16x32_bf16 v[114:117], v[158:161], v[166:169], v[114:117]
	v_mfma_f32_16x16x32_bf16 v[102:105], v[150:153], v[174:177], v[102:105]
	v_mfma_f32_16x16x32_bf16 v[98:101], v[158:161], v[174:177], v[98:101]
	v_mfma_f32_16x16x32_bf16 v[86:89], v[150:153], v[182:185], v[86:89]
	v_mfma_f32_16x16x32_bf16 v[80:83], v[158:161], v[182:185], v[80:83]
	v_mfma_f32_16x16x32_bf16 v[68:71], v[150:153], v[190:193], v[68:71]
	v_mfma_f32_16x16x32_bf16 v[64:67], v[158:161], v[190:193], v[64:67]
	s_barrier
	s_add_i32 s59, s50, s33
	v_lshl_add_u64 v[194:195], s[30:31], 0, v[212:213]
	s_mov_b32 m0, s59
	ds_read_b128 v[162:165], v241 offset:16384
	ds_read_b128 v[166:169], v246 offset:16384
	ds_read_b128 v[170:173], v241 offset:18432
	ds_read_b128 v[174:177], v246 offset:18432
	ds_read_b128 v[178:181], v241 offset:20480
	ds_read_b128 v[182:185], v246 offset:20480
	ds_read_b128 v[186:189], v241 offset:22528
	ds_read_b128 v[190:193], v246 offset:22528
	global_load_lds_dwordx4 v[194:195], off
	s_add_i32 m0, s59, 0x2000
	s_add_u32 s60, s30, 0x40000
	v_lshl_add_u64 v[196:197], s[30:31], 0, v[216:217]
	s_addc_u32 s61, s31, 0
	s_add_i32 s59, s51, s33
	global_load_lds_dwordx4 v[196:197], off
	v_lshl_add_u64 v[84:85], s[60:61], 0, v[212:213]
	s_mov_b32 m0, s59
	v_lshl_add_u64 v[198:199], s[34:35], 0, v[210:211]
	global_load_lds_dwordx4 v[84:85], off
	v_lshl_add_u64 v[84:85], s[60:61], 0, v[216:217]
	s_add_i32 m0, s59, 0x2000
	v_lshl_add_u64 v[200:201], s[34:35], 0, v[214:215]
	global_load_lds_dwordx4 v[84:85], off
	s_mov_b32 m0, s36
	s_nop 0
	global_load_lds_dwordx4 v[198:199], off
	s_mov_b32 m0, s37
	s_nop 0
	global_load_lds_dwordx4 v[200:201], off
	s_waitcnt vmcnt(8)
	s_waitcnt lgkmcnt(0)
	s_barrier
	s_waitcnt lgkmcnt(0)
	v_mfma_f32_16x16x32_bf16 v[60:63], v[130:133], v[162:165], 0
	v_mfma_f32_16x16x32_bf16 v[56:59], v[138:141], v[162:165], 0
	v_mfma_f32_16x16x32_bf16 v[44:47], v[130:133], v[170:173], 0
	v_mfma_f32_16x16x32_bf16 v[40:43], v[138:141], v[170:173], 0
	v_mfma_f32_16x16x32_bf16 v[28:31], v[130:133], v[178:181], 0
	v_mfma_f32_16x16x32_bf16 v[24:27], v[138:141], v[178:181], 0
	v_mfma_f32_16x16x32_bf16 v[12:15], v[130:133], v[186:189], 0
	v_mfma_f32_16x16x32_bf16 v[8:11], v[138:141], v[186:189], 0
	v_mfma_f32_16x16x32_bf16 v[60:63], v[134:137], v[166:169], v[60:63]
	v_mfma_f32_16x16x32_bf16 v[56:59], v[142:145], v[166:169], v[56:59]
	v_mfma_f32_16x16x32_bf16 v[44:47], v[134:137], v[174:177], v[44:47]
	v_mfma_f32_16x16x32_bf16 v[40:43], v[142:145], v[174:177], v[40:43]
	v_mfma_f32_16x16x32_bf16 v[28:31], v[134:137], v[182:185], v[28:31]
	v_mfma_f32_16x16x32_bf16 v[24:27], v[142:145], v[182:185], v[24:27]
	v_mfma_f32_16x16x32_bf16 v[12:15], v[134:137], v[190:193], v[12:15]
	v_mfma_f32_16x16x32_bf16 v[8:11], v[142:145], v[190:193], v[8:11]
	v_mfma_f32_16x16x32_bf16 v[52:55], v[146:149], v[162:165], 0
	v_mfma_f32_16x16x32_bf16 v[48:51], v[154:157], v[162:165], 0
	v_mfma_f32_16x16x32_bf16 v[36:39], v[146:149], v[170:173], 0
	v_mfma_f32_16x16x32_bf16 v[32:35], v[154:157], v[170:173], 0
	v_mfma_f32_16x16x32_bf16 v[20:23], v[146:149], v[178:181], 0
	v_mfma_f32_16x16x32_bf16 v[16:19], v[154:157], v[178:181], 0
	v_mfma_f32_16x16x32_bf16 v[4:7], v[146:149], v[186:189], 0
	v_mfma_f32_16x16x32_bf16 v[0:3], v[154:157], v[186:189], 0
	v_mfma_f32_16x16x32_bf16 v[52:55], v[150:153], v[166:169], v[52:55]
	v_mfma_f32_16x16x32_bf16 v[48:51], v[158:161], v[166:169], v[48:51]
	v_mfma_f32_16x16x32_bf16 v[36:39], v[150:153], v[174:177], v[36:39]
	v_mfma_f32_16x16x32_bf16 v[32:35], v[158:161], v[174:177], v[32:35]
	v_mfma_f32_16x16x32_bf16 v[20:23], v[150:153], v[182:185], v[20:23]
	v_mfma_f32_16x16x32_bf16 v[16:19], v[158:161], v[182:185], v[16:19]
	v_mfma_f32_16x16x32_bf16 v[4:7], v[150:153], v[190:193], v[4:7]
	v_mfma_f32_16x16x32_bf16 v[0:3], v[158:161], v[190:193], v[0:3]
	s_barrier
	s_add_i32 s59, 0, 0x18000
	v_add_u32_e32 v84, s59, v237
	v_add_u32_e32 v250, s59, v247
	s_add_i32 s60, 0, 0x1c000
	ds_read_b128 v[130:133], v84
	ds_read_b128 v[134:137], v250
	ds_read_b128 v[138:141], v84 offset:2048
	ds_read_b128 v[142:145], v250 offset:2048
	v_add_u32_e32 v84, s60, v237
	v_add_u32_e32 v251, s60, v247
	ds_read_b128 v[146:149], v84
	ds_read_b128 v[150:153], v251
	ds_read_b128 v[154:157], v84 offset:2048
	ds_read_b128 v[158:161], v251 offset:2048
	s_add_u32 s34, s34, 0x40000
	s_addc_u32 s35, s35, 0
	s_mov_b32 m0, s38
	v_lshl_add_u64 v[84:85], s[34:35], 0, v[210:211]
	ds_read_b128 v[162:165], v241 offset:32768
	ds_read_b128 v[166:169], v246 offset:32768
	ds_read_b128 v[170:173], v241 offset:34816
	ds_read_b128 v[174:177], v246 offset:34816
	ds_read_b128 v[178:181], v241 offset:36864
	ds_read_b128 v[182:185], v246 offset:36864
	ds_read_b128 v[186:189], v241 offset:38912
	ds_read_b128 v[190:193], v246 offset:38912
	global_load_lds_dwordx4 v[84:85], off
	v_lshl_add_u64 v[84:85], s[34:35], 0, v[214:215]
	s_mov_b32 m0, s39
	s_nop 0
	global_load_lds_dwordx4 v[84:85], off
	s_waitcnt vmcnt(8)
	s_waitcnt lgkmcnt(0)
	s_barrier
	s_waitcnt lgkmcnt(0)
	v_mfma_f32_16x16x32_bf16 v[126:129], v[130:133], v[162:165], v[126:129]
	v_mfma_f32_16x16x32_bf16 v[122:125], v[138:141], v[162:165], v[122:125]
	v_mfma_f32_16x16x32_bf16 v[110:113], v[130:133], v[170:173], v[110:113]
	v_mfma_f32_16x16x32_bf16 v[106:109], v[138:141], v[170:173], v[106:109]
	v_mfma_f32_16x16x32_bf16 v[94:97], v[130:133], v[178:181], v[94:97]
	v_mfma_f32_16x16x32_bf16 v[90:93], v[138:141], v[178:181], v[90:93]
	v_mfma_f32_16x16x32_bf16 v[76:79], v[130:133], v[186:189], v[76:79]
	v_mfma_f32_16x16x32_bf16 v[72:75], v[138:141], v[186:189], v[72:75]
	v_mfma_f32_16x16x32_bf16 v[126:129], v[134:137], v[166:169], v[126:129]
	v_mfma_f32_16x16x32_bf16 v[122:125], v[142:145], v[166:169], v[122:125]
	v_mfma_f32_16x16x32_bf16 v[110:113], v[134:137], v[174:177], v[110:113]
	v_mfma_f32_16x16x32_bf16 v[106:109], v[142:145], v[174:177], v[106:109]
	v_mfma_f32_16x16x32_bf16 v[94:97], v[134:137], v[182:185], v[94:97]
	v_mfma_f32_16x16x32_bf16 v[90:93], v[142:145], v[182:185], v[90:93]
	v_mfma_f32_16x16x32_bf16 v[76:79], v[134:137], v[190:193], v[76:79]
	v_mfma_f32_16x16x32_bf16 v[72:75], v[142:145], v[190:193], v[72:75]
	v_mfma_f32_16x16x32_bf16 v[118:121], v[146:149], v[162:165], v[118:121]
	v_mfma_f32_16x16x32_bf16 v[114:117], v[154:157], v[162:165], v[114:117]
	v_mfma_f32_16x16x32_bf16 v[102:105], v[146:149], v[170:173], v[102:105]
	v_mfma_f32_16x16x32_bf16 v[98:101], v[154:157], v[170:173], v[98:101]
	v_mfma_f32_16x16x32_bf16 v[84:87], v[146:149], v[178:181], v[86:89]
	v_mfma_f32_16x16x32_bf16 v[80:83], v[154:157], v[178:181], v[80:83]
	v_mfma_f32_16x16x32_bf16 v[68:71], v[146:149], v[186:189], v[68:71]
	v_mfma_f32_16x16x32_bf16 v[64:67], v[154:157], v[186:189], v[64:67]
	v_mfma_f32_16x16x32_bf16 v[118:121], v[150:153], v[166:169], v[118:121]
	v_mfma_f32_16x16x32_bf16 v[114:117], v[158:161], v[166:169], v[114:117]
	v_mfma_f32_16x16x32_bf16 v[102:105], v[150:153], v[174:177], v[102:105]
	v_mfma_f32_16x16x32_bf16 v[98:101], v[158:161], v[174:177], v[98:101]
	v_mfma_f32_16x16x32_bf16 v[86:89], v[150:153], v[182:185], v[84:87]
	v_mfma_f32_16x16x32_bf16 v[82:85], v[158:161], v[182:185], v[80:83]
	v_mfma_f32_16x16x32_bf16 v[68:71], v[150:153], v[190:193], v[68:71]
	v_mfma_f32_16x16x32_bf16 v[64:67], v[158:161], v[190:193], v[64:67]
	s_barrier
	s_add_i32 s34, s59, s33
	v_lshl_add_u64 v[80:81], v[194:195], 0, s[16:17]
	s_mov_b32 m0, s34
	ds_read_b128 v[162:165], v241 offset:49152
	ds_read_b128 v[166:169], v246 offset:49152
	ds_read_b128 v[170:173], v241 offset:51200
	ds_read_b128 v[174:177], v246 offset:51200
	ds_read_b128 v[178:181], v241 offset:53248
	ds_read_b128 v[182:185], v246 offset:53248
	ds_read_b128 v[186:189], v241 offset:55296
	ds_read_b128 v[190:193], v246 offset:55296
	global_load_lds_dwordx4 v[80:81], off
	s_add_i32 m0, s34, 0x2000
	s_add_u32 s30, s30, 0x40080
	v_lshl_add_u64 v[80:81], v[196:197], 0, s[16:17]
	s_addc_u32 s31, s31, 0
	s_add_i32 s34, s60, s33
	global_load_lds_dwordx4 v[80:81], off
	v_lshl_add_u64 v[80:81], s[30:31], 0, v[212:213]
	s_mov_b32 m0, s34
	s_nop 0
	global_load_lds_dwordx4 v[80:81], off
	v_lshl_add_u64 v[80:81], s[30:31], 0, v[216:217]
	s_add_i32 m0, s34, 0x2000
	s_nop 0
	global_load_lds_dwordx4 v[80:81], off
	v_lshl_add_u64 v[80:81], v[198:199], 0, s[16:17]
	s_mov_b32 m0, s47
	s_nop 0
	global_load_lds_dwordx4 v[80:81], off
	v_lshl_add_u64 v[80:81], v[200:201], 0, s[16:17]
	s_mov_b32 m0, s48
	s_nop 0
	global_load_lds_dwordx4 v[80:81], off
	s_waitcnt vmcnt(8)
	s_waitcnt lgkmcnt(0)
	s_barrier
	s_waitcnt lgkmcnt(0)
	v_mfma_f32_16x16x32_bf16 v[60:63], v[130:133], v[162:165], v[60:63]
	v_mfma_f32_16x16x32_bf16 v[56:59], v[138:141], v[162:165], v[56:59]
	v_mfma_f32_16x16x32_bf16 v[44:47], v[130:133], v[170:173], v[44:47]
	v_mfma_f32_16x16x32_bf16 v[40:43], v[138:141], v[170:173], v[40:43]
	v_mfma_f32_16x16x32_bf16 v[28:31], v[130:133], v[178:181], v[28:31]
	v_mfma_f32_16x16x32_bf16 v[24:27], v[138:141], v[178:181], v[24:27]
	v_mfma_f32_16x16x32_bf16 v[12:15], v[130:133], v[186:189], v[12:15]
	v_mfma_f32_16x16x32_bf16 v[8:11], v[138:141], v[186:189], v[8:11]
	v_mfma_f32_16x16x32_bf16 v[60:63], v[134:137], v[166:169], v[60:63]
	v_mfma_f32_16x16x32_bf16 v[56:59], v[142:145], v[166:169], v[56:59]
	v_mfma_f32_16x16x32_bf16 v[44:47], v[134:137], v[174:177], v[44:47]
	v_mfma_f32_16x16x32_bf16 v[40:43], v[142:145], v[174:177], v[40:43]
	v_mfma_f32_16x16x32_bf16 v[28:31], v[134:137], v[182:185], v[28:31]
	v_mfma_f32_16x16x32_bf16 v[24:27], v[142:145], v[182:185], v[24:27]
	v_mfma_f32_16x16x32_bf16 v[12:15], v[134:137], v[190:193], v[12:15]
	v_mfma_f32_16x16x32_bf16 v[8:11], v[142:145], v[190:193], v[8:11]
	v_mfma_f32_16x16x32_bf16 v[52:55], v[146:149], v[162:165], v[52:55]
	v_mfma_f32_16x16x32_bf16 v[48:51], v[154:157], v[162:165], v[48:51]
	v_mfma_f32_16x16x32_bf16 v[36:39], v[146:149], v[170:173], v[36:39]
	v_mfma_f32_16x16x32_bf16 v[32:35], v[154:157], v[170:173], v[32:35]
	v_mfma_f32_16x16x32_bf16 v[20:23], v[146:149], v[178:181], v[20:23]
	v_mfma_f32_16x16x32_bf16 v[16:19], v[154:157], v[178:181], v[16:19]
	v_mfma_f32_16x16x32_bf16 v[4:7], v[146:149], v[186:189], v[4:7]
	v_mfma_f32_16x16x32_bf16 v[0:3], v[154:157], v[186:189], v[0:3]
	v_mfma_f32_16x16x32_bf16 v[52:55], v[150:153], v[166:169], v[52:55]
	v_mfma_f32_16x16x32_bf16 v[48:51], v[158:161], v[166:169], v[48:51]
	v_mfma_f32_16x16x32_bf16 v[36:39], v[150:153], v[174:177], v[36:39]
	v_mfma_f32_16x16x32_bf16 v[32:35], v[158:161], v[174:177], v[32:35]
	v_mfma_f32_16x16x32_bf16 v[20:23], v[150:153], v[182:185], v[20:23]
	v_mfma_f32_16x16x32_bf16 v[16:19], v[158:161], v[182:185], v[16:19]
	v_mfma_f32_16x16x32_bf16 v[4:7], v[150:153], v[190:193], v[4:7]
	v_mfma_f32_16x16x32_bf16 v[0:3], v[158:161], v[190:193], v[0:3]
	s_barrier
	s_add_i32 s58, s58, 2
	s_add_u32 s28, s28, 0x100
	s_addc_u32 s29, s29, 0
	s_add_u32 s56, s56, 0x100
	s_addc_u32 s57, s57, 0
	s_cmp_gt_u32 s58, 13
	.p2align 6

.LBB0_670:
	s_waitcnt lgkmcnt(0)
	s_barrier
	s_add_u32 s94, s94, 0x20000
	v_lshl_add_u64 v[92:93], v[92:93], 0, s[72:73]
	s_addc_u32 s95, s95, 0
	v_lshl_add_u64 v[94:95], v[94:95], 0, s[66:67]
	s_andn2_b64 vcc, exec, s[4:5]
	v_add_u32_e32 v156, 0x400, v156
	s_cbranch_vccz .LBB0_612
	.p2align 6

.Lat_nomask_230:
	v_max3_f32 v2, v96, v97, v112
	v_max3_f32 v3, v98, v99, v113
	v_max3_f32 v2, v2, v114, v115
	v_max3_f32 v2, v2, v100, v101
	v_max3_f32 v3, v3, v102, v103
	v_max3_f32 v2, v2, v116, v117
	v_max3_f32 v3, v3, v118, v119
	v_max3_f32 v2, v2, v104, v105
	v_max3_f32 v3, v3, v106, v107
	v_max3_f32 v2, v2, v120, v121
	v_max3_f32 v3, v3, v122, v123
	v_max3_f32 v2, v2, v108, v109
	v_max3_f32 v3, v3, v110, v111
	v_max3_f32 v2, v2, v124, v125
	v_max3_f32 v3, v3, v126, v127
	v_max_f32_e32 v2, v2, v3
	v_mov_b32_e32 v3, v2
	s_nop 1
	v_permlane32_swap_b32_e32 v2, v3
	v_max_f32_e32 v2, v2, v3
	v_mov_b32_e32 v4, v2
	s_mov_b64 s[68:69], 0
	v_add_f32_e32 v248, v248, v4
	v_sub_f32_e32 v96, v96, v4
	v_sub_f32_e32 v97, v97, v4
	v_sub_f32_e32 v98, v98, v4
	v_sub_f32_e32 v99, v99, v4
	v_sub_f32_e32 v100, v100, v4
	v_sub_f32_e32 v101, v101, v4
	v_sub_f32_e32 v102, v102, v4
	v_sub_f32_e32 v103, v103, v4
	v_sub_f32_e32 v104, v104, v4
	v_sub_f32_e32 v105, v105, v4
	v_sub_f32_e32 v106, v106, v4
	v_sub_f32_e32 v107, v107, v4
	v_sub_f32_e32 v108, v108, v4
	v_sub_f32_e32 v109, v109, v4
	v_sub_f32_e32 v110, v110, v4
	v_sub_f32_e32 v111, v111, v4
	v_sub_f32_e32 v112, v112, v4
	v_sub_f32_e32 v113, v113, v4
	v_sub_f32_e32 v114, v114, v4
	v_sub_f32_e32 v115, v115, v4
	v_sub_f32_e32 v116, v116, v4
	v_sub_f32_e32 v117, v117, v4
	v_sub_f32_e32 v118, v118, v4
	v_sub_f32_e32 v119, v119, v4
	v_sub_f32_e32 v120, v120, v4
	v_sub_f32_e32 v121, v121, v4
	v_sub_f32_e32 v122, v122, v4
	v_sub_f32_e32 v123, v123, v4
	v_sub_f32_e32 v124, v124, v4
	v_sub_f32_e32 v125, v125, v4
	v_sub_f32_e32 v126, v126, v4
	v_sub_f32_e32 v127, v127, v4
	v_xor_b32_e32 v5, 0x80000000, v248
	v_mov_b32_e32 v160, v5
	v_mov_b32_e32 v161, v5
	v_mov_b32_e32 v162, v5
	v_mov_b32_e32 v163, v5
	v_mov_b32_e32 v164, v5
	v_mov_b32_e32 v165, v5
	v_mov_b32_e32 v166, v5
	v_mov_b32_e32 v167, v5
	v_mov_b32_e32 v168, v5
	v_mov_b32_e32 v169, v5
	v_mov_b32_e32 v170, v5
	v_mov_b32_e32 v171, v5
	v_mov_b32_e32 v172, v5
	v_mov_b32_e32 v173, v5
	v_mov_b32_e32 v174, v5
	v_mov_b32_e32 v175, v5
	v_exp_f32_e32 v96, v96
	v_exp_f32_e32 v97, v97
	v_exp_f32_e32 v98, v98
	v_exp_f32_e32 v99, v99
	v_exp_f32_e32 v100, v100
	v_exp_f32_e32 v101, v101
	v_exp_f32_e32 v102, v102
	v_exp_f32_e32 v103, v103
	v_exp_f32_e32 v104, v104
	v_exp_f32_e32 v105, v105
	v_exp_f32_e32 v106, v106
	v_exp_f32_e32 v107, v107
	v_exp_f32_e32 v108, v108
	v_exp_f32_e32 v109, v109
	v_exp_f32_e32 v110, v110
	v_exp_f32_e32 v111, v111
	v_exp_f32_e32 v112, v112
	v_exp_f32_e32 v113, v113
	v_exp_f32_e32 v114, v114
	v_exp_f32_e32 v115, v115
	v_exp_f32_e32 v116, v116
	v_exp_f32_e32 v117, v117
	v_exp_f32_e32 v118, v118
	v_exp_f32_e32 v119, v119
	v_exp_f32_e32 v120, v120
	v_exp_f32_e32 v121, v121
	v_exp_f32_e32 v122, v122
	v_exp_f32_e32 v123, v123
	v_exp_f32_e32 v124, v124
	v_exp_f32_e32 v125, v125
	v_exp_f32_e32 v126, v126
	v_exp_f32_e32 v127, v127
	s_waitcnt vmcnt(0) lgkmcnt(0)
	s_barrier
	s_add_i32 m0, s57, s70
	s_nop 0
	global_load_lds_dwordx4 v238, s[74:75]
	s_add_u32 s74, s74, 0x10000
	s_addc_u32 s75, s75, 0
	s_lshl_b32 s60, s58, 1
	s_add_i32 s60, s60, s71
	s_mov_b32 m0, s60
	s_nop 0
	global_load_lds_dwordx4 v239, s[76:77]
	s_add_u32 s62, s76, 0x80
	s_addc_u32 s63, s77, 0
	s_add_i32 m0, s60, 0x2000
	s_nop 0
	global_load_lds_dwordx4 v239, s[62:63]
	s_add_u32 s76, s76, 0x10000
	s_addc_u32 s77, s77, 0
	s_mov_b32 s67, s56
	s_mov_b32 s56, s57
	s_mov_b32 s57, s58
	s_mov_b32 s58, s67
	v_add_u32_e32 v250, s57, v244
	ds_read_b128 v[208:211], v250
	ds_read_b128 v[212:215], v250 offset:512
	ds_read_b128 v[216:219], v250 offset:2048
	ds_read_b128 v[220:223], v250 offset:2560
	ds_read_b128 v[224:227], v250 offset:4096
	ds_read_b128 v[228:231], v250 offset:4608
	ds_read_b128 v[232:235], v250 offset:6144
	ds_read_b128 v[240:243], v250 offset:6656
	s_mov_b32 s46, 1
	s_waitcnt vmcnt(3) lgkmcnt(0)
	s_barrier
	.p2align 6

.LBB0_1025:
	s_ashr_i32 s23, s22, 31
	s_lshl_b64 s[24:25], s[22:23], 19
	s_add_u32 s24, s90, s24
	s_addc_u32 s25, s91, s25
	s_and_b64 s[26:27], s[6:7], exec
	s_cselect_b32 s23, s25, s35
	s_cselect_b32 s29, s24, s34
	s_ashr_i32 s21, s20, 31
	s_lshl_b64 s[26:27], s[20:21], 19
	s_add_u32 s26, s2, s26
	s_addc_u32 s27, s3, s27
	s_and_b64 s[38:39], s[6:7], exec
	s_cselect_b32 s21, s27, s37
	s_cselect_b32 s55, s26, s36
	s_add_u32 s34, s34, 0x40080
	s_addc_u32 s35, s35, 0
	s_add_u32 s56, s36, 0x100
	s_addc_u32 s57, s37, 0
	s_mov_b32 s58, -2
	s_waitcnt lgkmcnt(0)
	s_waitcnt vmcnt(0)
	v_xor_b32_e32 v246, 64, v189
	v_xor_b32_e32 v247, 64, v185
	v_add_u32_e32 v248, s53, v247
	v_add_u32_e32 v249, s54, v247
	ds_read_b128 v[128:131], v187
	ds_read_b128 v[132:135], v248
	ds_read_b128 v[152:155], v187 offset:2048
	ds_read_b128 v[156:159], v248 offset:2048
	ds_read_b128 v[160:163], v188
	ds_read_b128 v[164:167], v249
	ds_read_b128 v[168:171], v188 offset:2048
	ds_read_b128 v[172:175], v249 offset:2048
	s_add_u32 s36, s34, 0xfffc0080
	s_addc_u32 s37, s35, -1
	s_cmp_eq_u32 s58, 12
	s_cselect_b32 s39, s23, s37
	s_cselect_b32 s38, s29, s36
	s_cselect_b32 s37, s21, s57
	s_cselect_b32 s36, s55, s56
	v_lshl_add_u64 v[216:217], s[34:35], 0, v[144:145]
	s_add_i32 m0, s31, 0xc000
	ds_read_b128 v[176:179], v189
	ds_read_b128 v[180:183], v246
	ds_read_b128 v[192:195], v189 offset:2048
	ds_read_b128 v[196:199], v246 offset:2048
	ds_read_b128 v[200:203], v189 offset:4096
	ds_read_b128 v[204:207], v246 offset:4096
	ds_read_b128 v[208:211], v189 offset:6144
	ds_read_b128 v[212:215], v246 offset:6144
	global_load_lds_dwordx4 v[216:217], off
	v_lshl_add_u64 v[216:217], s[34:35], 0, v[146:147]
	s_add_i32 m0, s31, 0xe000
	s_nop 0
	global_load_lds_dwordx4 v[216:217], off
	s_waitcnt vmcnt(8)
	s_waitcnt lgkmcnt(0)
	s_barrier
	s_waitcnt lgkmcnt(0)
	v_mfma_f32_16x16x32_bf16 v[124:127], v[128:131], v[176:179], 0
	v_mfma_f32_16x16x32_bf16 v[120:123], v[152:155], v[176:179], 0
	v_mfma_f32_16x16x32_bf16 v[108:111], v[128:131], v[192:195], 0
	v_mfma_f32_16x16x32_bf16 v[104:107], v[152:155], v[192:195], 0
	v_mfma_f32_16x16x32_bf16 v[92:95], v[128:131], v[200:203], 0
	v_mfma_f32_16x16x32_bf16 v[88:91], v[152:155], v[200:203], 0
	v_mfma_f32_16x16x32_bf16 v[76:79], v[128:131], v[208:211], 0
	v_mfma_f32_16x16x32_bf16 v[72:75], v[152:155], v[208:211], 0
	v_mfma_f32_16x16x32_bf16 v[124:127], v[132:135], v[180:183], v[124:127]
	v_mfma_f32_16x16x32_bf16 v[120:123], v[156:159], v[180:183], v[120:123]
	v_mfma_f32_16x16x32_bf16 v[108:111], v[132:135], v[196:199], v[108:111]
	v_mfma_f32_16x16x32_bf16 v[104:107], v[156:159], v[196:199], v[104:107]
	v_mfma_f32_16x16x32_bf16 v[92:95], v[132:135], v[204:207], v[92:95]
	v_mfma_f32_16x16x32_bf16 v[88:91], v[156:159], v[204:207], v[88:91]
	v_mfma_f32_16x16x32_bf16 v[76:79], v[132:135], v[212:215], v[76:79]
	v_mfma_f32_16x16x32_bf16 v[72:75], v[156:159], v[212:215], v[72:75]
	v_mfma_f32_16x16x32_bf16 v[116:119], v[160:163], v[176:179], 0
	v_mfma_f32_16x16x32_bf16 v[112:115], v[168:171], v[176:179], 0
	v_mfma_f32_16x16x32_bf16 v[100:103], v[160:163], v[192:195], 0
	v_mfma_f32_16x16x32_bf16 v[96:99], v[168:171], v[192:195], 0
	v_mfma_f32_16x16x32_bf16 v[84:87], v[160:163], v[200:203], 0
	v_mfma_f32_16x16x32_bf16 v[80:83], v[168:171], v[200:203], 0
	v_mfma_f32_16x16x32_bf16 v[68:71], v[160:163], v[208:211], 0
	v_mfma_f32_16x16x32_bf16 v[64:67], v[168:171], v[208:211], 0
	v_mfma_f32_16x16x32_bf16 v[116:119], v[164:167], v[180:183], v[116:119]
	v_mfma_f32_16x16x32_bf16 v[112:115], v[172:175], v[180:183], v[112:115]
	v_mfma_f32_16x16x32_bf16 v[100:103], v[164:167], v[196:199], v[100:103]
	v_mfma_f32_16x16x32_bf16 v[96:99], v[172:175], v[196:199], v[96:99]
	v_mfma_f32_16x16x32_bf16 v[84:87], v[164:167], v[204:207], v[84:87]
	v_mfma_f32_16x16x32_bf16 v[80:83], v[172:175], v[204:207], v[80:83]
	v_mfma_f32_16x16x32_bf16 v[68:71], v[164:167], v[212:215], v[68:71]
	v_mfma_f32_16x16x32_bf16 v[64:67], v[172:175], v[212:215], v[64:67]
	s_barrier
	s_add_i32 s59, s53, s33
	v_lshl_add_u64 v[216:217], s[36:37], 0, v[138:139]
	s_mov_b32 m0, s59
	ds_read_b128 v[176:179], v189 offset:16384
	ds_read_b128 v[180:183], v246 offset:16384
	ds_read_b128 v[192:195], v189 offset:18432
	ds_read_b128 v[196:199], v246 offset:18432
	ds_read_b128 v[200:203], v189 offset:20480
	ds_read_b128 v[204:207], v246 offset:20480
	ds_read_b128 v[208:211], v189 offset:22528
	ds_read_b128 v[212:215], v246 offset:22528
	global_load_lds_dwordx4 v[216:217], off
	s_add_i32 m0, s59, 0x2000
	s_add_u32 s60, s36, 0x40000
	v_lshl_add_u64 v[218:219], s[36:37], 0, v[142:143]
	s_addc_u32 s61, s37, 0
	s_add_i32 s59, s54, s33
	global_load_lds_dwordx4 v[218:219], off
	v_lshl_add_u64 v[220:221], s[60:61], 0, v[138:139]
	s_mov_b32 m0, s59
	v_lshl_add_u64 v[222:223], s[38:39], 0, v[140:141]
	global_load_lds_dwordx4 v[220:221], off
	v_lshl_add_u64 v[220:221], s[60:61], 0, v[142:143]
	s_add_i32 m0, s59, 0x2000
	s_nop 0
	global_load_lds_dwordx4 v[220:221], off
	v_lshl_add_u64 v[220:221], s[38:39], 0, v[136:137]
	s_mov_b32 m0, s31
	s_nop 0
	global_load_lds_dwordx4 v[220:221], off
	s_mov_b32 m0, s40
	s_nop 0
	global_load_lds_dwordx4 v[222:223], off
	s_waitcnt vmcnt(8)
	s_waitcnt lgkmcnt(0)
	s_barrier
	s_waitcnt lgkmcnt(0)
	v_mfma_f32_16x16x32_bf16 v[60:63], v[128:131], v[176:179], 0
	v_mfma_f32_16x16x32_bf16 v[56:59], v[152:155], v[176:179], 0
	v_mfma_f32_16x16x32_bf16 v[44:47], v[128:131], v[192:195], 0
	v_mfma_f32_16x16x32_bf16 v[40:43], v[152:155], v[192:195], 0
	v_mfma_f32_16x16x32_bf16 v[28:31], v[128:131], v[200:203], 0
	v_mfma_f32_16x16x32_bf16 v[24:27], v[152:155], v[200:203], 0
	v_mfma_f32_16x16x32_bf16 v[12:15], v[128:131], v[208:211], 0
	v_mfma_f32_16x16x32_bf16 v[8:11], v[152:155], v[208:211], 0
	v_mfma_f32_16x16x32_bf16 v[60:63], v[132:135], v[180:183], v[60:63]
	v_mfma_f32_16x16x32_bf16 v[56:59], v[156:159], v[180:183], v[56:59]
	v_mfma_f32_16x16x32_bf16 v[44:47], v[132:135], v[196:199], v[44:47]
	v_mfma_f32_16x16x32_bf16 v[40:43], v[156:159], v[196:199], v[40:43]
	v_mfma_f32_16x16x32_bf16 v[28:31], v[132:135], v[204:207], v[28:31]
	v_mfma_f32_16x16x32_bf16 v[24:27], v[156:159], v[204:207], v[24:27]
	v_mfma_f32_16x16x32_bf16 v[12:15], v[132:135], v[212:215], v[12:15]
	v_mfma_f32_16x16x32_bf16 v[8:11], v[156:159], v[212:215], v[8:11]
	v_mfma_f32_16x16x32_bf16 v[52:55], v[160:163], v[176:179], 0
	v_mfma_f32_16x16x32_bf16 v[48:51], v[168:171], v[176:179], 0
	v_mfma_f32_16x16x32_bf16 v[36:39], v[160:163], v[192:195], 0
	v_mfma_f32_16x16x32_bf16 v[32:35], v[168:171], v[192:195], 0
	v_mfma_f32_16x16x32_bf16 v[20:23], v[160:163], v[200:203], 0
	v_mfma_f32_16x16x32_bf16 v[16:19], v[168:171], v[200:203], 0
	v_mfma_f32_16x16x32_bf16 v[4:7], v[160:163], v[208:211], 0
	v_mfma_f32_16x16x32_bf16 v[0:3], v[168:171], v[208:211], 0
	v_mfma_f32_16x16x32_bf16 v[52:55], v[164:167], v[180:183], v[52:55]
	v_mfma_f32_16x16x32_bf16 v[48:51], v[172:175], v[180:183], v[48:51]
	v_mfma_f32_16x16x32_bf16 v[36:39], v[164:167], v[196:199], v[36:39]
	v_mfma_f32_16x16x32_bf16 v[32:35], v[172:175], v[196:199], v[32:35]
	v_mfma_f32_16x16x32_bf16 v[20:23], v[164:167], v[204:207], v[20:23]
	v_mfma_f32_16x16x32_bf16 v[16:19], v[172:175], v[204:207], v[16:19]
	v_mfma_f32_16x16x32_bf16 v[4:7], v[164:167], v[212:215], v[4:7]
	v_mfma_f32_16x16x32_bf16 v[0:3], v[172:175], v[212:215], v[0:3]
	s_barrier
	s_add_i32 s59, 0, 0x18000
	s_add_i32 s60, 0, 0x1c000
	v_add_u32_e32 v156, s59, v185
	v_add_u32_e32 v250, s59, v247
	v_add_u32_e32 v172, s60, v185
	v_add_u32_e32 v251, s60, v247
	ds_read_b128 v[128:131], v156
	ds_read_b128 v[132:135], v250
	ds_read_b128 v[152:155], v156 offset:2048
	ds_read_b128 v[156:159], v250 offset:2048
	ds_read_b128 v[160:163], v172
	ds_read_b128 v[164:167], v251
	ds_read_b128 v[168:171], v172 offset:2048
	ds_read_b128 v[172:175], v251 offset:2048
	s_add_u32 s38, s38, 0x40000
	s_addc_u32 s39, s39, 0
	s_mov_b32 m0, s41
	v_lshl_add_u64 v[224:225], s[38:39], 0, v[136:137]
	ds_read_b128 v[176:179], v189 offset:32768
	ds_read_b128 v[180:183], v246 offset:32768
	ds_read_b128 v[192:195], v189 offset:34816
	ds_read_b128 v[196:199], v246 offset:34816
	ds_read_b128 v[200:203], v189 offset:36864
	ds_read_b128 v[204:207], v246 offset:36864
	ds_read_b128 v[208:211], v189 offset:38912
	ds_read_b128 v[212:215], v246 offset:38912
	global_load_lds_dwordx4 v[224:225], off
	v_lshl_add_u64 v[224:225], s[38:39], 0, v[140:141]
	s_mov_b32 m0, s42
	s_nop 0
	global_load_lds_dwordx4 v[224:225], off
	s_waitcnt vmcnt(8)
	s_waitcnt lgkmcnt(0)
	s_barrier
	s_waitcnt lgkmcnt(0)
	v_mfma_f32_16x16x32_bf16 v[124:127], v[128:131], v[176:179], v[124:127]
	v_mfma_f32_16x16x32_bf16 v[120:123], v[152:155], v[176:179], v[120:123]
	v_mfma_f32_16x16x32_bf16 v[108:111], v[128:131], v[192:195], v[108:111]
	v_mfma_f32_16x16x32_bf16 v[104:107], v[152:155], v[192:195], v[104:107]
	v_mfma_f32_16x16x32_bf16 v[92:95], v[128:131], v[200:203], v[92:95]
	v_mfma_f32_16x16x32_bf16 v[88:91], v[152:155], v[200:203], v[88:91]
	v_mfma_f32_16x16x32_bf16 v[76:79], v[128:131], v[208:211], v[76:79]
	v_mfma_f32_16x16x32_bf16 v[72:75], v[152:155], v[208:211], v[72:75]
	v_mfma_f32_16x16x32_bf16 v[124:127], v[132:135], v[180:183], v[124:127]
	v_mfma_f32_16x16x32_bf16 v[120:123], v[156:159], v[180:183], v[120:123]
	v_mfma_f32_16x16x32_bf16 v[108:111], v[132:135], v[196:199], v[108:111]
	v_mfma_f32_16x16x32_bf16 v[104:107], v[156:159], v[196:199], v[104:107]
	v_mfma_f32_16x16x32_bf16 v[92:95], v[132:135], v[204:207], v[92:95]
	v_mfma_f32_16x16x32_bf16 v[88:91], v[156:159], v[204:207], v[88:91]
	v_mfma_f32_16x16x32_bf16 v[76:79], v[132:135], v[212:215], v[76:79]
	v_mfma_f32_16x16x32_bf16 v[72:75], v[156:159], v[212:215], v[72:75]
	v_mfma_f32_16x16x32_bf16 v[116:119], v[160:163], v[176:179], v[116:119]
	v_mfma_f32_16x16x32_bf16 v[112:115], v[168:171], v[176:179], v[112:115]
	v_mfma_f32_16x16x32_bf16 v[100:103], v[160:163], v[192:195], v[100:103]
	v_mfma_f32_16x16x32_bf16 v[96:99], v[168:171], v[192:195], v[96:99]
	v_mfma_f32_16x16x32_bf16 v[84:87], v[160:163], v[200:203], v[84:87]
	v_mfma_f32_16x16x32_bf16 v[80:83], v[168:171], v[200:203], v[80:83]
	v_mfma_f32_16x16x32_bf16 v[68:71], v[160:163], v[208:211], v[68:71]
	v_mfma_f32_16x16x32_bf16 v[64:67], v[168:171], v[208:211], v[64:67]
	v_mfma_f32_16x16x32_bf16 v[116:119], v[164:167], v[180:183], v[116:119]
	v_mfma_f32_16x16x32_bf16 v[112:115], v[172:175], v[180:183], v[112:115]
	v_mfma_f32_16x16x32_bf16 v[100:103], v[164:167], v[196:199], v[100:103]
	v_mfma_f32_16x16x32_bf16 v[96:99], v[172:175], v[196:199], v[96:99]
	v_mfma_f32_16x16x32_bf16 v[84:87], v[164:167], v[204:207], v[84:87]
	v_mfma_f32_16x16x32_bf16 v[80:83], v[172:175], v[204:207], v[80:83]
	v_mfma_f32_16x16x32_bf16 v[68:71], v[164:167], v[212:215], v[68:71]
	v_mfma_f32_16x16x32_bf16 v[64:67], v[172:175], v[212:215], v[64:67]
	s_barrier
	s_add_i32 s38, s59, s33
	v_lshl_add_u64 v[216:217], v[216:217], 0, s[16:17]
	s_mov_b32 m0, s38
	ds_read_b128 v[176:179], v189 offset:49152
	ds_read_b128 v[180:183], v246 offset:49152
	ds_read_b128 v[192:195], v189 offset:51200
	ds_read_b128 v[196:199], v246 offset:51200
	ds_read_b128 v[200:203], v189 offset:53248
	ds_read_b128 v[204:207], v246 offset:53248
	ds_read_b128 v[208:211], v189 offset:55296
	ds_read_b128 v[212:215], v246 offset:55296
	global_load_lds_dwordx4 v[216:217], off
	s_add_i32 m0, s38, 0x2000
	s_add_u32 s36, s36, 0x40080
	v_lshl_add_u64 v[216:217], v[218:219], 0, s[16:17]
	s_addc_u32 s37, s37, 0
	s_add_i32 s38, s60, s33
	global_load_lds_dwordx4 v[216:217], off
	v_lshl_add_u64 v[216:217], s[36:37], 0, v[138:139]
	s_mov_b32 m0, s38
	s_nop 0
	global_load_lds_dwordx4 v[216:217], off
	v_lshl_add_u64 v[216:217], s[36:37], 0, v[142:143]
	s_add_i32 m0, s38, 0x2000
	s_nop 0
	global_load_lds_dwordx4 v[216:217], off
	v_lshl_add_u64 v[216:217], v[220:221], 0, s[16:17]
	s_mov_b32 m0, s48
	s_nop 0
	global_load_lds_dwordx4 v[216:217], off
	v_lshl_add_u64 v[216:217], v[222:223], 0, s[16:17]
	s_mov_b32 m0, s49
	s_nop 0
	global_load_lds_dwordx4 v[216:217], off
	s_waitcnt vmcnt(8)
	s_waitcnt lgkmcnt(0)
	s_barrier
	s_waitcnt lgkmcnt(0)
	v_mfma_f32_16x16x32_bf16 v[60:63], v[128:131], v[176:179], v[60:63]
	v_mfma_f32_16x16x32_bf16 v[56:59], v[152:155], v[176:179], v[56:59]
	v_mfma_f32_16x16x32_bf16 v[44:47], v[128:131], v[192:195], v[44:47]
	v_mfma_f32_16x16x32_bf16 v[40:43], v[152:155], v[192:195], v[40:43]
	v_mfma_f32_16x16x32_bf16 v[28:31], v[128:131], v[200:203], v[28:31]
	v_mfma_f32_16x16x32_bf16 v[24:27], v[152:155], v[200:203], v[24:27]
	v_mfma_f32_16x16x32_bf16 v[12:15], v[128:131], v[208:211], v[12:15]
	v_mfma_f32_16x16x32_bf16 v[8:11], v[152:155], v[208:211], v[8:11]
	v_mfma_f32_16x16x32_bf16 v[60:63], v[132:135], v[180:183], v[60:63]
	v_mfma_f32_16x16x32_bf16 v[56:59], v[156:159], v[180:183], v[56:59]
	v_mfma_f32_16x16x32_bf16 v[44:47], v[132:135], v[196:199], v[44:47]
	v_mfma_f32_16x16x32_bf16 v[40:43], v[156:159], v[196:199], v[40:43]
	v_mfma_f32_16x16x32_bf16 v[28:31], v[132:135], v[204:207], v[28:31]
	v_mfma_f32_16x16x32_bf16 v[24:27], v[156:159], v[204:207], v[24:27]
	v_mfma_f32_16x16x32_bf16 v[12:15], v[132:135], v[212:215], v[12:15]
	v_mfma_f32_16x16x32_bf16 v[8:11], v[156:159], v[212:215], v[8:11]
	v_mfma_f32_16x16x32_bf16 v[52:55], v[160:163], v[176:179], v[52:55]
	v_mfma_f32_16x16x32_bf16 v[48:51], v[168:171], v[176:179], v[48:51]
	v_mfma_f32_16x16x32_bf16 v[36:39], v[160:163], v[192:195], v[36:39]
	v_mfma_f32_16x16x32_bf16 v[32:35], v[168:171], v[192:195], v[32:35]
	v_mfma_f32_16x16x32_bf16 v[20:23], v[160:163], v[200:203], v[20:23]
	v_mfma_f32_16x16x32_bf16 v[16:19], v[168:171], v[200:203], v[16:19]
	v_mfma_f32_16x16x32_bf16 v[4:7], v[160:163], v[208:211], v[4:7]
	v_mfma_f32_16x16x32_bf16 v[0:3], v[168:171], v[208:211], v[0:3]
	v_mfma_f32_16x16x32_bf16 v[52:55], v[164:167], v[180:183], v[52:55]
	v_mfma_f32_16x16x32_bf16 v[48:51], v[172:175], v[180:183], v[48:51]
	v_mfma_f32_16x16x32_bf16 v[36:39], v[164:167], v[196:199], v[36:39]
	v_mfma_f32_16x16x32_bf16 v[32:35], v[172:175], v[196:199], v[32:35]
	v_mfma_f32_16x16x32_bf16 v[20:23], v[164:167], v[204:207], v[20:23]
	v_mfma_f32_16x16x32_bf16 v[16:19], v[172:175], v[204:207], v[16:19]
	v_mfma_f32_16x16x32_bf16 v[4:7], v[164:167], v[212:215], v[4:7]
	v_mfma_f32_16x16x32_bf16 v[0:3], v[172:175], v[212:215], v[0:3]
	s_barrier
	s_add_i32 s58, s58, 2
	s_add_u32 s34, s34, 0x100
	s_addc_u32 s35, s35, 0
	s_add_u32 s56, s56, 0x100
	s_addc_u32 s57, s57, 0
	s_cmp_gt_u32 s58, 13
	.p2align 6

.LBB0_1110:
	s_add_u32 s24, s24, 0x40080
	s_addc_u32 s25, s25, 0
	s_add_u32 s53, s26, 0x100
	s_addc_u32 s54, s27, 0
	s_mov_b32 s55, -2
	s_waitcnt vmcnt(0)
	v_xor_b32_e32 v246, 64, v179
	v_xor_b32_e32 v247, 64, v167
	v_add_u32_e32 v248, s46, v247
	v_add_u32_e32 v249, s47, v247
	ds_read_b128 v[124:127], v171
	ds_read_b128 v[132:135], v248
	ds_read_b128 v[136:139], v171 offset:2048
	ds_read_b128 v[140:143], v248 offset:2048
	ds_read_b128 v[162:165], v175
	ds_read_b128 v[182:185], v249
	ds_read_b128 v[186:189], v175 offset:2048
	ds_read_b128 v[190:193], v249 offset:2048
	s_add_u32 s26, s24, 0xfffc0080
	s_addc_u32 s27, s25, -1
	s_cmp_eq_u32 s55, 12
	s_cselect_b32 s29, s17, s27
	s_cselect_b32 s28, s51, s26
	s_cselect_b32 s27, s15, s54
	s_cselect_b32 s26, s52, s53
	v_lshl_add_u64 v[172:173], s[24:25], 0, v[152:153]
	s_add_i32 m0, s23, 0xc000
	ds_read_b128 v[194:197], v179
	ds_read_b128 v[198:201], v246
	ds_read_b128 v[202:205], v179 offset:2048
	ds_read_b128 v[206:209], v246 offset:2048
	ds_read_b128 v[210:213], v179 offset:4096
	ds_read_b128 v[214:217], v246 offset:4096
	ds_read_b128 v[218:221], v179 offset:6144
	ds_read_b128 v[222:225], v246 offset:6144
	global_load_lds_dwordx4 v[172:173], off
	v_lshl_add_u64 v[172:173], s[24:25], 0, v[154:155]
	s_add_i32 m0, s23, 0xe000
	s_nop 0
	global_load_lds_dwordx4 v[172:173], off
	s_waitcnt vmcnt(8)
	s_waitcnt lgkmcnt(0)
	s_barrier
	s_waitcnt lgkmcnt(0)
	v_mfma_f32_16x16x32_bf16 v[128:131], v[124:127], v[194:197], 0
	s_add_i32 s39, s39, 1
	s_mul_i32 s0, s39, s42
	s_mul_hi_u32 s1, s39, s45
	v_mfma_f32_16x16x32_bf16 v[120:123], v[136:139], v[194:197], 0
	s_add_i32 s1, s1, s0
	s_mul_i32 s0, s39, s45
	s_add_u32 s18, s0, s96
	v_mfma_f32_16x16x32_bf16 v[108:111], v[124:127], v[202:205], 0
	s_addc_u32 s19, s1, s34
	v_cmp_lt_i64_e64 s[0:1], s[18:19], v[156:157]
	s_ashr_i32 s14, s18, 31
	v_mfma_f32_16x16x32_bf16 v[104:107], v[136:139], v[202:205], 0
	s_lshr_b32 s14, s14, 29
	s_add_i32 s14, s18, s14
	s_ashr_i32 s15, s14, 3
	v_mfma_f32_16x16x32_bf16 v[92:95], v[124:127], v[210:213], 0
	s_and_b32 s14, s14, -8
	s_sub_i32 s14, s18, s14
	s_cmp_lt_i32 s14, 0
	v_mfma_f32_16x16x32_bf16 v[88:91], v[136:139], v[210:213], 0
	s_cselect_b32 s16, s35, 0x160
	s_mul_i32 s14, s14, s16
	s_add_i32 s14, s14, s15
	v_mfma_f32_16x16x32_bf16 v[76:79], v[124:127], v[218:221], 0
	s_mul_hi_i32 s15, s14, 0x2e8ba2e9
	s_lshr_b32 s16, s15, 31
	s_ashr_i32 s15, s15, 5
	v_mfma_f32_16x16x32_bf16 v[72:75], v[136:139], v[218:221], 0
	s_add_i32 s15, s15, s16
	s_lshl_b32 s16, s15, 3
	s_sub_i32 s17, 0x80, s16
	v_mfma_f32_16x16x32_bf16 v[128:131], v[132:135], v[198:201], v[128:131]
	s_min_i32 s17, s17, 8
	s_abs_i32 s18, s17
	v_cvt_f32_u32_e32 v252, s18
	v_mfma_f32_16x16x32_bf16 v[120:123], v[140:143], v[198:201], v[120:123]
	s_sub_i32 s20, 0, s18
	s_mulk_i32 s15, 0xb0
	s_sub_i32 s15, s14, s15
	v_mfma_f32_16x16x32_bf16 v[108:111], v[132:135], v[206:209], v[108:111]
	v_rcp_iflag_f32_e32 v252, v252
	s_abs_i32 s14, s15
	s_xor_b32 s19, s15, s17
	v_mfma_f32_16x16x32_bf16 v[104:107], v[140:143], v[206:209], v[104:107]
	s_ashr_i32 s19, s19, 31
	v_mul_f32_e32 v252, 0x4f7ffffe, v252
	v_cvt_u32_f32_e32 v252, v252
	v_mfma_f32_16x16x32_bf16 v[92:95], v[132:135], v[214:217], v[92:95]
	s_nop 0
	v_readfirstlane_b32 s21, v252
	s_mul_i32 s20, s20, s21
	v_mfma_f32_16x16x32_bf16 v[88:91], v[140:143], v[214:217], v[88:91]
	s_mul_hi_u32 s20, s21, s20
	s_add_i32 s21, s21, s20
	s_mul_hi_u32 s20, s14, s21
	v_mfma_f32_16x16x32_bf16 v[76:79], v[132:135], v[222:225], v[76:79]
	s_mul_i32 s21, s20, s18
	s_sub_i32 s14, s14, s21
	s_add_i32 s98, s20, 1
	v_mfma_f32_16x16x32_bf16 v[72:75], v[140:143], v[222:225], v[72:75]
	s_sub_i32 s21, s14, s18
	s_cmp_ge_u32 s14, s18
	s_cselect_b32 s20, s98, s20
	v_mfma_f32_16x16x32_bf16 v[116:119], v[162:165], v[194:197], 0
	s_cselect_b32 s14, s21, s14
	s_add_i32 s21, s20, 1
	s_cmp_ge_u32 s14, s18
	v_mfma_f32_16x16x32_bf16 v[112:115], v[186:189], v[194:197], 0
	s_cselect_b32 s14, s21, s20
	s_xor_b32 s14, s14, s19
	s_sub_i32 s14, s14, s19
	v_mfma_f32_16x16x32_bf16 v[100:103], v[162:165], v[202:205], 0
	s_mul_i32 s17, s14, s17
	s_sub_i32 s15, s15, s17
	s_add_i32 s16, s16, s15
	v_mfma_f32_16x16x32_bf16 v[96:99], v[186:189], v[202:205], 0
	s_ashr_i32 s17, s16, 31
	s_lshl_b64 s[18:19], s[16:17], 19
	s_add_u32 s18, s2, s18
	v_mfma_f32_16x16x32_bf16 v[84:87], v[162:165], v[210:213], 0
	s_addc_u32 s19, s3, s19
	s_and_b64 s[20:21], s[0:1], exec
	s_cselect_b32 s17, s19, s25
	v_mfma_f32_16x16x32_bf16 v[80:83], v[186:189], v[210:213], 0
	s_cselect_b32 s51, s18, s24
	s_ashr_i32 s15, s14, 31
	s_lshl_b64 s[20:21], s[14:15], 19
	v_mfma_f32_16x16x32_bf16 v[68:71], v[162:165], v[218:221], 0
	s_add_u32 s20, s30, s20
	s_addc_u32 s21, s31, s21
	s_and_b64 s[98:99], s[0:1], exec
	v_mfma_f32_16x16x32_bf16 v[64:67], v[186:189], v[218:221], 0
	s_cselect_b32 s15, s21, s27
	s_cselect_b32 s52, s20, s26
	v_mfma_f32_16x16x32_bf16 v[116:119], v[182:185], v[198:201], v[116:119]
	v_mfma_f32_16x16x32_bf16 v[112:115], v[190:193], v[198:201], v[112:115]
	v_mfma_f32_16x16x32_bf16 v[100:103], v[182:185], v[206:209], v[100:103]
	v_mfma_f32_16x16x32_bf16 v[96:99], v[190:193], v[206:209], v[96:99]
	v_mfma_f32_16x16x32_bf16 v[84:87], v[182:185], v[214:217], v[84:87]
	v_mfma_f32_16x16x32_bf16 v[80:83], v[190:193], v[214:217], v[80:83]
	v_mfma_f32_16x16x32_bf16 v[68:71], v[182:185], v[222:225], v[68:71]
	v_mfma_f32_16x16x32_bf16 v[64:67], v[190:193], v[222:225], v[64:67]
	s_barrier
	s_add_i32 s56, s46, s33
	v_lshl_add_u64 v[172:173], s[26:27], 0, v[148:149]
	s_mov_b32 m0, s56
	ds_read_b128 v[194:197], v179 offset:16384
	ds_read_b128 v[198:201], v246 offset:16384
	ds_read_b128 v[202:205], v179 offset:18432
	ds_read_b128 v[206:209], v246 offset:18432
	ds_read_b128 v[210:213], v179 offset:20480
	ds_read_b128 v[214:217], v246 offset:20480
	ds_read_b128 v[218:221], v179 offset:22528
	ds_read_b128 v[222:225], v246 offset:22528
	global_load_lds_dwordx4 v[172:173], off
	s_add_i32 m0, s56, 0x2000
	s_add_u32 s56, s26, 0x40000
	v_lshl_add_u64 v[176:177], s[26:27], 0, v[144:145]
	s_addc_u32 s57, s27, 0
	s_add_i32 s58, s47, s33
	global_load_lds_dwordx4 v[176:177], off
	v_lshl_add_u64 v[226:227], s[56:57], 0, v[148:149]
	s_mov_b32 m0, s58
	v_lshl_add_u64 v[228:229], s[28:29], 0, v[146:147]
	global_load_lds_dwordx4 v[226:227], off
	v_lshl_add_u64 v[226:227], s[56:57], 0, v[144:145]
	s_add_i32 m0, s58, 0x2000
	s_nop 0
	global_load_lds_dwordx4 v[226:227], off
	v_lshl_add_u64 v[226:227], s[28:29], 0, v[150:151]
	s_mov_b32 m0, s23
	s_nop 0
	global_load_lds_dwordx4 v[226:227], off
	s_mov_b32 m0, s36
	s_nop 0
	global_load_lds_dwordx4 v[228:229], off
	s_waitcnt vmcnt(8)
	s_waitcnt lgkmcnt(0)
	s_barrier
	s_waitcnt lgkmcnt(0)
	v_mfma_f32_16x16x32_bf16 v[60:63], v[124:127], v[194:197], 0
	v_mfma_f32_16x16x32_bf16 v[56:59], v[136:139], v[194:197], 0
	v_mfma_f32_16x16x32_bf16 v[44:47], v[124:127], v[202:205], 0
	v_mfma_f32_16x16x32_bf16 v[40:43], v[136:139], v[202:205], 0
	v_mfma_f32_16x16x32_bf16 v[28:31], v[124:127], v[210:213], 0
	v_mfma_f32_16x16x32_bf16 v[24:27], v[136:139], v[210:213], 0
	v_mfma_f32_16x16x32_bf16 v[12:15], v[124:127], v[218:221], 0
	v_mfma_f32_16x16x32_bf16 v[8:11], v[136:139], v[218:221], 0
	v_mfma_f32_16x16x32_bf16 v[60:63], v[132:135], v[198:201], v[60:63]
	v_mfma_f32_16x16x32_bf16 v[56:59], v[140:143], v[198:201], v[56:59]
	v_mfma_f32_16x16x32_bf16 v[44:47], v[132:135], v[206:209], v[44:47]
	v_mfma_f32_16x16x32_bf16 v[40:43], v[140:143], v[206:209], v[40:43]
	v_mfma_f32_16x16x32_bf16 v[28:31], v[132:135], v[214:217], v[28:31]
	v_mfma_f32_16x16x32_bf16 v[24:27], v[140:143], v[214:217], v[24:27]
	v_mfma_f32_16x16x32_bf16 v[12:15], v[132:135], v[222:225], v[12:15]
	v_mfma_f32_16x16x32_bf16 v[8:11], v[140:143], v[222:225], v[8:11]
	v_mfma_f32_16x16x32_bf16 v[52:55], v[162:165], v[194:197], 0
	v_mfma_f32_16x16x32_bf16 v[48:51], v[186:189], v[194:197], 0
	v_mfma_f32_16x16x32_bf16 v[36:39], v[162:165], v[202:205], 0
	v_mfma_f32_16x16x32_bf16 v[32:35], v[186:189], v[202:205], 0
	v_mfma_f32_16x16x32_bf16 v[20:23], v[162:165], v[210:213], 0
	v_mfma_f32_16x16x32_bf16 v[16:19], v[186:189], v[210:213], 0
	v_mfma_f32_16x16x32_bf16 v[4:7], v[162:165], v[218:221], 0
	v_mfma_f32_16x16x32_bf16 v[0:3], v[186:189], v[218:221], 0
	v_mfma_f32_16x16x32_bf16 v[52:55], v[182:185], v[198:201], v[52:55]
	v_mfma_f32_16x16x32_bf16 v[48:51], v[190:193], v[198:201], v[48:51]
	v_mfma_f32_16x16x32_bf16 v[36:39], v[182:185], v[206:209], v[36:39]
	v_mfma_f32_16x16x32_bf16 v[32:35], v[190:193], v[206:209], v[32:35]
	v_mfma_f32_16x16x32_bf16 v[20:23], v[182:185], v[214:217], v[20:23]
	v_mfma_f32_16x16x32_bf16 v[16:19], v[190:193], v[214:217], v[16:19]
	v_mfma_f32_16x16x32_bf16 v[4:7], v[182:185], v[222:225], v[4:7]
	v_mfma_f32_16x16x32_bf16 v[0:3], v[190:193], v[222:225], v[0:3]
	s_barrier
	s_add_i32 s56, 0, 0x18000
	s_add_i32 s57, 0, 0x1c000
	v_add_u32_e32 v140, s56, v167
	v_add_u32_e32 v250, s56, v247
	v_add_u32_e32 v160, s57, v167
	v_add_u32_e32 v251, s57, v247
	ds_read_b128 v[124:127], v140
	ds_read_b128 v[132:135], v250
	ds_read_b128 v[136:139], v140 offset:2048
	ds_read_b128 v[140:143], v250 offset:2048
	ds_read_b128 v[162:165], v160
	ds_read_b128 v[182:185], v251
	ds_read_b128 v[186:189], v160 offset:2048
	ds_read_b128 v[190:193], v251 offset:2048
	s_add_u32 s28, s28, 0x40000
	s_addc_u32 s29, s29, 0
	s_mov_b32 m0, s37
	v_lshl_add_u64 v[230:231], s[28:29], 0, v[150:151]
	ds_read_b128 v[194:197], v179 offset:32768
	ds_read_b128 v[198:201], v246 offset:32768
	ds_read_b128 v[202:205], v179 offset:34816
	ds_read_b128 v[206:209], v246 offset:34816
	ds_read_b128 v[210:213], v179 offset:36864
	ds_read_b128 v[214:217], v246 offset:36864
	ds_read_b128 v[218:221], v179 offset:38912
	ds_read_b128 v[222:225], v246 offset:38912
	global_load_lds_dwordx4 v[230:231], off
	v_lshl_add_u64 v[230:231], s[28:29], 0, v[146:147]
	s_mov_b32 m0, s38
	s_nop 0
	global_load_lds_dwordx4 v[230:231], off
	s_waitcnt vmcnt(8)
	s_waitcnt lgkmcnt(0)
	s_barrier
	s_waitcnt lgkmcnt(0)
	v_mfma_f32_16x16x32_bf16 v[128:131], v[124:127], v[194:197], v[128:131]
	v_mfma_f32_16x16x32_bf16 v[120:123], v[136:139], v[194:197], v[120:123]
	v_mfma_f32_16x16x32_bf16 v[108:111], v[124:127], v[202:205], v[108:111]
	v_mfma_f32_16x16x32_bf16 v[104:107], v[136:139], v[202:205], v[104:107]
	v_mfma_f32_16x16x32_bf16 v[92:95], v[124:127], v[210:213], v[92:95]
	v_mfma_f32_16x16x32_bf16 v[88:91], v[136:139], v[210:213], v[88:91]
	v_mfma_f32_16x16x32_bf16 v[76:79], v[124:127], v[218:221], v[76:79]
	v_mfma_f32_16x16x32_bf16 v[72:75], v[136:139], v[218:221], v[72:75]
	v_mfma_f32_16x16x32_bf16 v[128:131], v[132:135], v[198:201], v[128:131]
	v_mfma_f32_16x16x32_bf16 v[120:123], v[140:143], v[198:201], v[120:123]
	v_mfma_f32_16x16x32_bf16 v[108:111], v[132:135], v[206:209], v[108:111]
	v_mfma_f32_16x16x32_bf16 v[104:107], v[140:143], v[206:209], v[104:107]
	v_mfma_f32_16x16x32_bf16 v[92:95], v[132:135], v[214:217], v[92:95]
	v_mfma_f32_16x16x32_bf16 v[88:91], v[140:143], v[214:217], v[88:91]
	v_mfma_f32_16x16x32_bf16 v[76:79], v[132:135], v[222:225], v[76:79]
	v_mfma_f32_16x16x32_bf16 v[72:75], v[140:143], v[222:225], v[72:75]
	v_mfma_f32_16x16x32_bf16 v[116:119], v[162:165], v[194:197], v[116:119]
	v_mfma_f32_16x16x32_bf16 v[112:115], v[186:189], v[194:197], v[112:115]
	v_mfma_f32_16x16x32_bf16 v[100:103], v[162:165], v[202:205], v[100:103]
	v_mfma_f32_16x16x32_bf16 v[96:99], v[186:189], v[202:205], v[96:99]
	v_mfma_f32_16x16x32_bf16 v[84:87], v[162:165], v[210:213], v[84:87]
	v_mfma_f32_16x16x32_bf16 v[80:83], v[186:189], v[210:213], v[80:83]
	v_mfma_f32_16x16x32_bf16 v[68:71], v[162:165], v[218:221], v[68:71]
	v_mfma_f32_16x16x32_bf16 v[64:67], v[186:189], v[218:221], v[64:67]
	v_mfma_f32_16x16x32_bf16 v[116:119], v[182:185], v[198:201], v[116:119]
	v_mfma_f32_16x16x32_bf16 v[112:115], v[190:193], v[198:201], v[112:115]
	v_mfma_f32_16x16x32_bf16 v[100:103], v[182:185], v[206:209], v[100:103]
	v_mfma_f32_16x16x32_bf16 v[96:99], v[190:193], v[206:209], v[96:99]
	v_mfma_f32_16x16x32_bf16 v[84:87], v[182:185], v[214:217], v[84:87]
	v_mfma_f32_16x16x32_bf16 v[80:83], v[190:193], v[214:217], v[80:83]
	v_mfma_f32_16x16x32_bf16 v[68:71], v[182:185], v[222:225], v[68:71]
	v_mfma_f32_16x16x32_bf16 v[64:67], v[190:193], v[222:225], v[64:67]
	s_barrier
	s_add_i32 s28, s56, s33
	v_lshl_add_u64 v[172:173], v[172:173], 0, s[10:11]
	s_mov_b32 m0, s28
	ds_read_b128 v[194:197], v179 offset:49152
	ds_read_b128 v[198:201], v246 offset:49152
	ds_read_b128 v[202:205], v179 offset:51200
	ds_read_b128 v[206:209], v246 offset:51200
	ds_read_b128 v[210:213], v179 offset:53248
	ds_read_b128 v[214:217], v246 offset:53248
	ds_read_b128 v[218:221], v179 offset:55296
	ds_read_b128 v[222:225], v246 offset:55296
	global_load_lds_dwordx4 v[172:173], off
	s_add_i32 m0, s28, 0x2000
	s_add_u32 s26, s26, 0x40080
	v_lshl_add_u64 v[172:173], v[176:177], 0, s[10:11]
	s_addc_u32 s27, s27, 0
	s_add_i32 s28, s57, s33
	global_load_lds_dwordx4 v[172:173], off
	v_lshl_add_u64 v[172:173], s[26:27], 0, v[148:149]
	s_mov_b32 m0, s28
	s_nop 0
	global_load_lds_dwordx4 v[172:173], off
	v_lshl_add_u64 v[172:173], s[26:27], 0, v[144:145]
	s_add_i32 m0, s28, 0x2000
	s_nop 0
	global_load_lds_dwordx4 v[172:173], off
	v_lshl_add_u64 v[172:173], v[226:227], 0, s[10:11]
	s_mov_b32 m0, s43
	s_nop 0
	global_load_lds_dwordx4 v[172:173], off
	v_lshl_add_u64 v[172:173], v[228:229], 0, s[10:11]
	s_mov_b32 m0, s44
	s_nop 0
	global_load_lds_dwordx4 v[172:173], off
	s_waitcnt vmcnt(8)
	s_waitcnt lgkmcnt(0)
	s_barrier
	s_waitcnt lgkmcnt(0)
	v_mfma_f32_16x16x32_bf16 v[60:63], v[124:127], v[194:197], v[60:63]
	v_mfma_f32_16x16x32_bf16 v[56:59], v[136:139], v[194:197], v[56:59]
	v_mfma_f32_16x16x32_bf16 v[44:47], v[124:127], v[202:205], v[44:47]
	v_mfma_f32_16x16x32_bf16 v[40:43], v[136:139], v[202:205], v[40:43]
	v_mfma_f32_16x16x32_bf16 v[28:31], v[124:127], v[210:213], v[28:31]
	v_mfma_f32_16x16x32_bf16 v[24:27], v[136:139], v[210:213], v[24:27]
	v_mfma_f32_16x16x32_bf16 v[12:15], v[124:127], v[218:221], v[12:15]
	v_mfma_f32_16x16x32_bf16 v[8:11], v[136:139], v[218:221], v[8:11]
	v_mfma_f32_16x16x32_bf16 v[60:63], v[132:135], v[198:201], v[60:63]
	v_mfma_f32_16x16x32_bf16 v[56:59], v[140:143], v[198:201], v[56:59]
	v_mfma_f32_16x16x32_bf16 v[44:47], v[132:135], v[206:209], v[44:47]
	v_mfma_f32_16x16x32_bf16 v[40:43], v[140:143], v[206:209], v[40:43]
	v_mfma_f32_16x16x32_bf16 v[28:31], v[132:135], v[214:217], v[28:31]
	v_mfma_f32_16x16x32_bf16 v[24:27], v[140:143], v[214:217], v[24:27]
	v_mfma_f32_16x16x32_bf16 v[12:15], v[132:135], v[222:225], v[12:15]
	v_mfma_f32_16x16x32_bf16 v[8:11], v[140:143], v[222:225], v[8:11]
	v_mfma_f32_16x16x32_bf16 v[52:55], v[162:165], v[194:197], v[52:55]
	v_mfma_f32_16x16x32_bf16 v[48:51], v[186:189], v[194:197], v[48:51]
	v_mfma_f32_16x16x32_bf16 v[36:39], v[162:165], v[202:205], v[36:39]
	v_mfma_f32_16x16x32_bf16 v[32:35], v[186:189], v[202:205], v[32:35]
	v_mfma_f32_16x16x32_bf16 v[20:23], v[162:165], v[210:213], v[20:23]
	v_mfma_f32_16x16x32_bf16 v[16:19], v[186:189], v[210:213], v[16:19]
	v_mfma_f32_16x16x32_bf16 v[4:7], v[162:165], v[218:221], v[4:7]
	v_mfma_f32_16x16x32_bf16 v[0:3], v[186:189], v[218:221], v[0:3]
	v_mfma_f32_16x16x32_bf16 v[52:55], v[182:185], v[198:201], v[52:55]
	v_mfma_f32_16x16x32_bf16 v[48:51], v[190:193], v[198:201], v[48:51]
	v_mfma_f32_16x16x32_bf16 v[36:39], v[182:185], v[206:209], v[36:39]
	v_mfma_f32_16x16x32_bf16 v[32:35], v[190:193], v[206:209], v[32:35]
	v_mfma_f32_16x16x32_bf16 v[20:23], v[182:185], v[214:217], v[20:23]
	v_mfma_f32_16x16x32_bf16 v[16:19], v[190:193], v[214:217], v[16:19]
	v_mfma_f32_16x16x32_bf16 v[4:7], v[182:185], v[222:225], v[4:7]
	v_mfma_f32_16x16x32_bf16 v[0:3], v[190:193], v[222:225], v[0:3]
	s_barrier
	s_add_i32 s55, s55, 2
	s_add_u32 s24, s24, 0x100
	s_addc_u32 s25, s25, 0
	s_add_u32 s53, s53, 0x100
	s_addc_u32 s54, s54, 0
	s_cmp_gt_u32 s55, 13
	.p2align 6

.LBB0_1195:
	s_add_u32 s41, s16, 0x100
	s_addc_u32 s42, s17, 0
	s_mov_b32 s43, -2
	s_waitcnt vmcnt(0)
	v_xor_b32_e32 v246, 64, v173
	v_xor_b32_e32 v247, 64, v169
	v_add_u32_e32 v248, s35, v247
	v_add_u32_e32 v249, s36, v247
	ds_read_b128 v[144:147], v171
	ds_read_b128 v[148:151], v248
	ds_read_b128 v[152:155], v171 offset:2048
	ds_read_b128 v[156:159], v248 offset:2048
	ds_read_b128 v[160:163], v172
	ds_read_b128 v[164:167], v249
	ds_read_b128 v[174:177], v172 offset:2048
	ds_read_b128 v[178:181], v249 offset:2048
	s_add_u32 s16, s14, 0x100
	s_addc_u32 s17, s15, 0
	s_cmp_eq_u32 s43, 40
	s_cselect_b32 s21, s5, s17
	s_cselect_b32 s20, s4, s16
	s_cselect_b32 s19, s13, s42
	s_cselect_b32 s18, s12, s41
	v_lshl_add_u64 v[214:215], s[14:15], 0, v[136:137]
	s_add_i32 m0, s24, 0xc000
	ds_read_b128 v[182:185], v173
	ds_read_b128 v[186:189], v246
	ds_read_b128 v[190:193], v173 offset:2048
	ds_read_b128 v[194:197], v246 offset:2048
	ds_read_b128 v[198:201], v173 offset:4096
	ds_read_b128 v[202:205], v246 offset:4096
	ds_read_b128 v[206:209], v173 offset:6144
	ds_read_b128 v[210:213], v246 offset:6144
	global_load_lds_dwordx4 v[214:215], off
	v_lshl_add_u64 v[214:215], s[14:15], 0, v[138:139]
	s_add_i32 m0, s24, 0xe000
	s_nop 0
	global_load_lds_dwordx4 v[214:215], off
	s_waitcnt vmcnt(8)
	s_waitcnt lgkmcnt(0)
	s_barrier
	s_waitcnt lgkmcnt(0)
	v_mfma_f32_16x16x32_bf16 v[124:127], v[144:147], v[182:185], 0
	v_mfma_f32_16x16x32_bf16 v[120:123], v[152:155], v[182:185], 0
	v_mfma_f32_16x16x32_bf16 v[112:115], v[144:147], v[190:193], 0
	v_mfma_f32_16x16x32_bf16 v[104:107], v[152:155], v[190:193], 0
	v_mfma_f32_16x16x32_bf16 v[96:99], v[144:147], v[198:201], 0
	v_mfma_f32_16x16x32_bf16 v[88:91], v[152:155], v[198:201], 0
	v_mfma_f32_16x16x32_bf16 v[80:83], v[144:147], v[206:209], 0
	v_mfma_f32_16x16x32_bf16 v[72:75], v[152:155], v[206:209], 0
	v_mfma_f32_16x16x32_bf16 v[124:127], v[148:151], v[186:189], v[124:127]
	v_mfma_f32_16x16x32_bf16 v[120:123], v[156:159], v[186:189], v[120:123]
	v_mfma_f32_16x16x32_bf16 v[112:115], v[148:151], v[194:197], v[112:115]
	v_mfma_f32_16x16x32_bf16 v[104:107], v[156:159], v[194:197], v[104:107]
	v_mfma_f32_16x16x32_bf16 v[96:99], v[148:151], v[202:205], v[96:99]
	v_mfma_f32_16x16x32_bf16 v[88:91], v[156:159], v[202:205], v[88:91]
	v_mfma_f32_16x16x32_bf16 v[80:83], v[148:151], v[210:213], v[80:83]
	v_mfma_f32_16x16x32_bf16 v[72:75], v[156:159], v[210:213], v[72:75]
	v_mfma_f32_16x16x32_bf16 v[116:119], v[160:163], v[182:185], 0
	v_mfma_f32_16x16x32_bf16 v[108:111], v[174:177], v[182:185], 0
	v_mfma_f32_16x16x32_bf16 v[100:103], v[160:163], v[190:193], 0
	v_mfma_f32_16x16x32_bf16 v[92:95], v[174:177], v[190:193], 0
	v_mfma_f32_16x16x32_bf16 v[84:87], v[160:163], v[198:201], 0
	v_mfma_f32_16x16x32_bf16 v[76:79], v[174:177], v[198:201], 0
	v_mfma_f32_16x16x32_bf16 v[68:71], v[160:163], v[206:209], 0
	v_mfma_f32_16x16x32_bf16 v[64:67], v[174:177], v[206:209], 0
	v_mfma_f32_16x16x32_bf16 v[116:119], v[164:167], v[186:189], v[116:119]
	v_mfma_f32_16x16x32_bf16 v[108:111], v[178:181], v[186:189], v[108:111]
	v_mfma_f32_16x16x32_bf16 v[100:103], v[164:167], v[194:197], v[100:103]
	v_mfma_f32_16x16x32_bf16 v[92:95], v[178:181], v[194:197], v[92:95]
	v_mfma_f32_16x16x32_bf16 v[84:87], v[164:167], v[202:205], v[84:87]
	v_mfma_f32_16x16x32_bf16 v[76:79], v[178:181], v[202:205], v[76:79]
	v_mfma_f32_16x16x32_bf16 v[68:71], v[164:167], v[210:213], v[68:71]
	v_mfma_f32_16x16x32_bf16 v[64:67], v[178:181], v[210:213], v[64:67]
	s_barrier
	s_add_i32 s14, s35, s23
	v_lshl_add_u64 v[214:215], s[18:19], 0, v[130:131]
	s_mov_b32 m0, s14
	ds_read_b128 v[182:185], v173 offset:16384
	ds_read_b128 v[186:189], v246 offset:16384
	ds_read_b128 v[190:193], v173 offset:18432
	ds_read_b128 v[194:197], v246 offset:18432
	ds_read_b128 v[198:201], v173 offset:20480
	ds_read_b128 v[202:205], v246 offset:20480
	ds_read_b128 v[206:209], v173 offset:22528
	ds_read_b128 v[210:213], v246 offset:22528
	global_load_lds_dwordx4 v[214:215], off
	s_add_i32 m0, s14, 0x2000
	s_add_u32 s14, s18, 0xb0000
	v_lshl_add_u64 v[216:217], s[18:19], 0, v[134:135]
	s_addc_u32 s15, s19, 0
	s_add_i32 s44, s36, s23
	global_load_lds_dwordx4 v[216:217], off
	v_lshl_add_u64 v[218:219], s[14:15], 0, v[130:131]
	s_mov_b32 m0, s44
	v_lshl_add_u64 v[220:221], s[20:21], 0, v[132:133]
	global_load_lds_dwordx4 v[218:219], off
	v_lshl_add_u64 v[218:219], s[14:15], 0, v[134:135]
	s_add_i32 m0, s44, 0x2000
	s_nop 0
	global_load_lds_dwordx4 v[218:219], off
	v_lshl_add_u64 v[218:219], s[20:21], 0, v[128:129]
	s_mov_b32 m0, s24
	s_nop 0
	global_load_lds_dwordx4 v[218:219], off
	s_mov_b32 m0, s25
	s_nop 0
	global_load_lds_dwordx4 v[220:221], off
	s_waitcnt vmcnt(8)
	s_waitcnt lgkmcnt(0)
	s_barrier
	s_waitcnt lgkmcnt(0)
	v_mfma_f32_16x16x32_bf16 v[60:63], v[144:147], v[182:185], 0
	v_mfma_f32_16x16x32_bf16 v[56:59], v[152:155], v[182:185], 0
	v_mfma_f32_16x16x32_bf16 v[48:51], v[144:147], v[190:193], 0
	v_mfma_f32_16x16x32_bf16 v[40:43], v[152:155], v[190:193], 0
	v_mfma_f32_16x16x32_bf16 v[32:35], v[144:147], v[198:201], 0
	v_mfma_f32_16x16x32_bf16 v[24:27], v[152:155], v[198:201], 0
	v_mfma_f32_16x16x32_bf16 v[16:19], v[144:147], v[206:209], 0
	v_mfma_f32_16x16x32_bf16 v[8:11], v[152:155], v[206:209], 0
	v_mfma_f32_16x16x32_bf16 v[60:63], v[148:151], v[186:189], v[60:63]
	v_mfma_f32_16x16x32_bf16 v[56:59], v[156:159], v[186:189], v[56:59]
	v_mfma_f32_16x16x32_bf16 v[48:51], v[148:151], v[194:197], v[48:51]
	v_mfma_f32_16x16x32_bf16 v[40:43], v[156:159], v[194:197], v[40:43]
	v_mfma_f32_16x16x32_bf16 v[32:35], v[148:151], v[202:205], v[32:35]
	v_mfma_f32_16x16x32_bf16 v[24:27], v[156:159], v[202:205], v[24:27]
	v_mfma_f32_16x16x32_bf16 v[16:19], v[148:151], v[210:213], v[16:19]
	v_mfma_f32_16x16x32_bf16 v[8:11], v[156:159], v[210:213], v[8:11]
	v_mfma_f32_16x16x32_bf16 v[52:55], v[160:163], v[182:185], 0
	v_mfma_f32_16x16x32_bf16 v[44:47], v[174:177], v[182:185], 0
	v_mfma_f32_16x16x32_bf16 v[36:39], v[160:163], v[190:193], 0
	v_mfma_f32_16x16x32_bf16 v[28:31], v[174:177], v[190:193], 0
	v_mfma_f32_16x16x32_bf16 v[20:23], v[160:163], v[198:201], 0
	v_mfma_f32_16x16x32_bf16 v[12:15], v[174:177], v[198:201], 0
	v_mfma_f32_16x16x32_bf16 v[4:7], v[160:163], v[206:209], 0
	v_mfma_f32_16x16x32_bf16 v[0:3], v[174:177], v[206:209], 0
	v_mfma_f32_16x16x32_bf16 v[52:55], v[164:167], v[186:189], v[52:55]
	v_mfma_f32_16x16x32_bf16 v[44:47], v[178:181], v[186:189], v[44:47]
	v_mfma_f32_16x16x32_bf16 v[36:39], v[164:167], v[194:197], v[36:39]
	v_mfma_f32_16x16x32_bf16 v[28:31], v[178:181], v[194:197], v[28:31]
	v_mfma_f32_16x16x32_bf16 v[20:23], v[164:167], v[202:205], v[20:23]
	v_mfma_f32_16x16x32_bf16 v[12:15], v[178:181], v[202:205], v[12:15]
	v_mfma_f32_16x16x32_bf16 v[4:7], v[164:167], v[210:213], v[4:7]
	v_mfma_f32_16x16x32_bf16 v[0:3], v[178:181], v[210:213], v[0:3]
	s_barrier
	s_add_i32 s44, 0, 0x18000
	s_add_i32 s45, 0, 0x1c000
	v_add_u32_e32 v156, s44, v169
	v_add_u32_e32 v250, s44, v247
	v_add_u32_e32 v178, s45, v169
	v_add_u32_e32 v251, s45, v247
	ds_read_b128 v[144:147], v156
	ds_read_b128 v[148:151], v250
	ds_read_b128 v[152:155], v156 offset:2048
	ds_read_b128 v[156:159], v250 offset:2048
	ds_read_b128 v[160:163], v178
	ds_read_b128 v[164:167], v251
	ds_read_b128 v[174:177], v178 offset:2048
	ds_read_b128 v[178:181], v251 offset:2048
	s_add_u32 s14, s20, 0xb0000
	s_addc_u32 s15, s21, 0
	s_mov_b32 m0, s26
	v_lshl_add_u64 v[222:223], s[14:15], 0, v[128:129]
	ds_read_b128 v[182:185], v173 offset:32768
	ds_read_b128 v[186:189], v246 offset:32768
	ds_read_b128 v[190:193], v173 offset:34816
	ds_read_b128 v[194:197], v246 offset:34816
	ds_read_b128 v[198:201], v173 offset:36864
	ds_read_b128 v[202:205], v246 offset:36864
	ds_read_b128 v[206:209], v173 offset:38912
	ds_read_b128 v[210:213], v246 offset:38912
	global_load_lds_dwordx4 v[222:223], off
	v_lshl_add_u64 v[222:223], s[14:15], 0, v[132:133]
	s_mov_b32 m0, s27
	s_nop 0
	global_load_lds_dwordx4 v[222:223], off
	s_waitcnt vmcnt(8)
	s_waitcnt lgkmcnt(0)
	s_barrier
	s_waitcnt lgkmcnt(0)
	v_mfma_f32_16x16x32_bf16 v[124:127], v[144:147], v[182:185], v[124:127]
	v_mfma_f32_16x16x32_bf16 v[120:123], v[152:155], v[182:185], v[120:123]
	v_mfma_f32_16x16x32_bf16 v[112:115], v[144:147], v[190:193], v[112:115]
	v_mfma_f32_16x16x32_bf16 v[104:107], v[152:155], v[190:193], v[104:107]
	v_mfma_f32_16x16x32_bf16 v[96:99], v[144:147], v[198:201], v[96:99]
	v_mfma_f32_16x16x32_bf16 v[88:91], v[152:155], v[198:201], v[88:91]
	v_mfma_f32_16x16x32_bf16 v[80:83], v[144:147], v[206:209], v[80:83]
	v_mfma_f32_16x16x32_bf16 v[72:75], v[152:155], v[206:209], v[72:75]
	v_mfma_f32_16x16x32_bf16 v[124:127], v[148:151], v[186:189], v[124:127]
	v_mfma_f32_16x16x32_bf16 v[120:123], v[156:159], v[186:189], v[120:123]
	v_mfma_f32_16x16x32_bf16 v[112:115], v[148:151], v[194:197], v[112:115]
	v_mfma_f32_16x16x32_bf16 v[104:107], v[156:159], v[194:197], v[104:107]
	v_mfma_f32_16x16x32_bf16 v[96:99], v[148:151], v[202:205], v[96:99]
	v_mfma_f32_16x16x32_bf16 v[88:91], v[156:159], v[202:205], v[88:91]
	v_mfma_f32_16x16x32_bf16 v[80:83], v[148:151], v[210:213], v[80:83]
	v_mfma_f32_16x16x32_bf16 v[72:75], v[156:159], v[210:213], v[72:75]
	v_mfma_f32_16x16x32_bf16 v[116:119], v[160:163], v[182:185], v[116:119]
	v_mfma_f32_16x16x32_bf16 v[108:111], v[174:177], v[182:185], v[108:111]
	v_mfma_f32_16x16x32_bf16 v[100:103], v[160:163], v[190:193], v[100:103]
	v_mfma_f32_16x16x32_bf16 v[92:95], v[174:177], v[190:193], v[92:95]
	v_mfma_f32_16x16x32_bf16 v[84:87], v[160:163], v[198:201], v[84:87]
	v_mfma_f32_16x16x32_bf16 v[76:79], v[174:177], v[198:201], v[76:79]
	v_mfma_f32_16x16x32_bf16 v[68:71], v[160:163], v[206:209], v[68:71]
	v_mfma_f32_16x16x32_bf16 v[64:67], v[174:177], v[206:209], v[64:67]
	v_mfma_f32_16x16x32_bf16 v[116:119], v[164:167], v[186:189], v[116:119]
	v_mfma_f32_16x16x32_bf16 v[108:111], v[178:181], v[186:189], v[108:111]
	v_mfma_f32_16x16x32_bf16 v[100:103], v[164:167], v[194:197], v[100:103]
	v_mfma_f32_16x16x32_bf16 v[92:95], v[178:181], v[194:197], v[92:95]
	v_mfma_f32_16x16x32_bf16 v[84:87], v[164:167], v[202:205], v[84:87]
	v_mfma_f32_16x16x32_bf16 v[76:79], v[178:181], v[202:205], v[76:79]
	v_mfma_f32_16x16x32_bf16 v[68:71], v[164:167], v[210:213], v[68:71]
	v_mfma_f32_16x16x32_bf16 v[64:67], v[178:181], v[210:213], v[64:67]
	s_barrier
	s_add_i32 s14, s44, s23
	v_lshl_add_u64 v[214:215], v[214:215], 0, s[8:9]
	s_mov_b32 m0, s14
	ds_read_b128 v[182:185], v173 offset:49152
	ds_read_b128 v[186:189], v246 offset:49152
	ds_read_b128 v[190:193], v173 offset:51200
	ds_read_b128 v[194:197], v246 offset:51200
	ds_read_b128 v[198:201], v173 offset:53248
	ds_read_b128 v[202:205], v246 offset:53248
	ds_read_b128 v[206:209], v173 offset:55296
	ds_read_b128 v[210:213], v246 offset:55296
	global_load_lds_dwordx4 v[214:215], off
	s_add_i32 m0, s14, 0x2000
	s_add_u32 s14, s18, 0xb0080
	v_lshl_add_u64 v[214:215], v[216:217], 0, s[8:9]
	s_addc_u32 s15, s19, 0
	s_add_i32 s18, s45, s23
	global_load_lds_dwordx4 v[214:215], off
	v_lshl_add_u64 v[214:215], s[14:15], 0, v[130:131]
	s_mov_b32 m0, s18
	s_nop 0
	global_load_lds_dwordx4 v[214:215], off
	v_lshl_add_u64 v[214:215], s[14:15], 0, v[134:135]
	s_add_i32 m0, s18, 0x2000
	s_nop 0
	global_load_lds_dwordx4 v[214:215], off
	v_lshl_add_u64 v[214:215], v[218:219], 0, s[8:9]
	s_mov_b32 m0, s31
	s_nop 0
	global_load_lds_dwordx4 v[214:215], off
	v_lshl_add_u64 v[214:215], v[220:221], 0, s[8:9]
	s_mov_b32 m0, s33
	s_nop 0
	global_load_lds_dwordx4 v[214:215], off
	s_waitcnt vmcnt(8)
	s_waitcnt lgkmcnt(0)
	s_barrier
	s_waitcnt lgkmcnt(0)
	v_mfma_f32_16x16x32_bf16 v[60:63], v[144:147], v[182:185], v[60:63]
	v_mfma_f32_16x16x32_bf16 v[56:59], v[152:155], v[182:185], v[56:59]
	v_mfma_f32_16x16x32_bf16 v[48:51], v[144:147], v[190:193], v[48:51]
	v_mfma_f32_16x16x32_bf16 v[40:43], v[152:155], v[190:193], v[40:43]
	v_mfma_f32_16x16x32_bf16 v[32:35], v[144:147], v[198:201], v[32:35]
	v_mfma_f32_16x16x32_bf16 v[24:27], v[152:155], v[198:201], v[24:27]
	v_mfma_f32_16x16x32_bf16 v[16:19], v[144:147], v[206:209], v[16:19]
	v_mfma_f32_16x16x32_bf16 v[8:11], v[152:155], v[206:209], v[8:11]
	v_mfma_f32_16x16x32_bf16 v[60:63], v[148:151], v[186:189], v[60:63]
	v_mfma_f32_16x16x32_bf16 v[56:59], v[156:159], v[186:189], v[56:59]
	v_mfma_f32_16x16x32_bf16 v[48:51], v[148:151], v[194:197], v[48:51]
	v_mfma_f32_16x16x32_bf16 v[40:43], v[156:159], v[194:197], v[40:43]
	v_mfma_f32_16x16x32_bf16 v[32:35], v[148:151], v[202:205], v[32:35]
	v_mfma_f32_16x16x32_bf16 v[24:27], v[156:159], v[202:205], v[24:27]
	v_mfma_f32_16x16x32_bf16 v[16:19], v[148:151], v[210:213], v[16:19]
	v_mfma_f32_16x16x32_bf16 v[8:11], v[156:159], v[210:213], v[8:11]
	v_mfma_f32_16x16x32_bf16 v[52:55], v[160:163], v[182:185], v[52:55]
	v_mfma_f32_16x16x32_bf16 v[44:47], v[174:177], v[182:185], v[44:47]
	v_mfma_f32_16x16x32_bf16 v[36:39], v[160:163], v[190:193], v[36:39]
	v_mfma_f32_16x16x32_bf16 v[28:31], v[174:177], v[190:193], v[28:31]
	v_mfma_f32_16x16x32_bf16 v[20:23], v[160:163], v[198:201], v[20:23]
	v_mfma_f32_16x16x32_bf16 v[12:15], v[174:177], v[198:201], v[12:15]
	v_mfma_f32_16x16x32_bf16 v[4:7], v[160:163], v[206:209], v[4:7]
	v_mfma_f32_16x16x32_bf16 v[0:3], v[174:177], v[206:209], v[0:3]
	v_mfma_f32_16x16x32_bf16 v[52:55], v[164:167], v[186:189], v[52:55]
	v_mfma_f32_16x16x32_bf16 v[44:47], v[178:181], v[186:189], v[44:47]
	v_mfma_f32_16x16x32_bf16 v[36:39], v[164:167], v[194:197], v[36:39]
	v_mfma_f32_16x16x32_bf16 v[28:31], v[178:181], v[194:197], v[28:31]
	v_mfma_f32_16x16x32_bf16 v[20:23], v[164:167], v[202:205], v[20:23]
	v_mfma_f32_16x16x32_bf16 v[12:15], v[178:181], v[202:205], v[12:15]
	v_mfma_f32_16x16x32_bf16 v[4:7], v[164:167], v[210:213], v[4:7]
	v_mfma_f32_16x16x32_bf16 v[0:3], v[178:181], v[210:213], v[0:3]
	s_barrier
	s_add_i32 s43, s43, 2
	s_add_u32 s41, s41, 0x100
	s_addc_u32 s42, s42, 0
	s_cmp_gt_u32 s43, 41
	s_mov_b64 s[14:15], s[16:17]
	.p2align 6
